# GEMM loops: 12 of 16 LDS-DMA per iteration use the SGPR-base + 32-bit VGPR offset form; 8 of their 16 64-bit VALU address adds per iteration deleted
# baseline (speedup 1.0000x reference)
.Llsb_skip_1:
.LBB0_335:
	ds_read_b128 v[128:131], v174
	ds_read_b128 v[132:135], v174 offset:1024
	ds_read_b128 v[158:161], v174 offset:2048
	ds_read_b128 v[178:181], v174 offset:3072
	ds_read_b128 v[182:185], v175
	ds_read_b128 v[186:189], v175 offset:1024
	ds_read_b128 v[190:193], v175 offset:2048
	ds_read_b128 v[194:197], v175 offset:3072
	s_add_u32 s28, s26, 0xfffc0080
	s_addc_u32 s29, s27, -1
	s_cmp_eq_u32 s56, 12
	s_cselect_b32 s31, s5, s29
	s_cselect_b32 s30, s21, s28
	s_cselect_b32 s29, s19, s55
	s_cselect_b32 s28, s53, s54
	s_add_i32 m0, s7, 0xc000
	ds_read_b128 v[198:201], v176
	ds_read_b128 v[206:209], v176 offset:1024
	ds_read_b128 v[210:213], v176 offset:2048
	ds_read_b128 v[214:217], v176 offset:3072
	ds_read_b128 v[218:221], v176 offset:4096
	ds_read_b128 v[222:225], v176 offset:5120
	ds_read_b128 v[226:229], v176 offset:6144
	ds_read_b128 v[230:233], v176 offset:7168
	global_load_lds_dwordx4 v150, s[26:27]
	s_add_i32 m0, s7, 0xe000
	s_nop 0
	global_load_lds_dwordx4 v152, s[26:27]
	s_waitcnt vmcnt(8)
	s_waitcnt lgkmcnt(0)
	s_barrier
	s_setprio 1
	s_waitcnt lgkmcnt(0)
	v_mfma_f32_16x16x32_bf16 v[124:127], v[128:131], v[198:201], v[124:127]
	v_mfma_f32_16x16x32_bf16 v[120:123], v[158:161], v[198:201], v[120:123]
	v_mfma_f32_16x16x32_bf16 v[108:111], v[128:131], v[210:213], v[108:111]
	v_mfma_f32_16x16x32_bf16 v[104:107], v[158:161], v[210:213], v[104:107]
	v_mfma_f32_16x16x32_bf16 v[92:95], v[128:131], v[218:221], v[92:95]
	v_mfma_f32_16x16x32_bf16 v[88:91], v[158:161], v[218:221], v[88:91]
	v_mfma_f32_16x16x32_bf16 v[76:79], v[128:131], v[226:229], v[76:79]
	v_mfma_f32_16x16x32_bf16 v[72:75], v[158:161], v[226:229], v[72:75]
	v_mfma_f32_16x16x32_bf16 v[124:127], v[132:135], v[206:209], v[124:127]
	v_mfma_f32_16x16x32_bf16 v[120:123], v[178:181], v[206:209], v[120:123]
	v_mfma_f32_16x16x32_bf16 v[108:111], v[132:135], v[214:217], v[108:111]
	v_mfma_f32_16x16x32_bf16 v[104:107], v[178:181], v[214:217], v[104:107]
	v_mfma_f32_16x16x32_bf16 v[92:95], v[132:135], v[222:225], v[92:95]
	v_mfma_f32_16x16x32_bf16 v[88:91], v[178:181], v[222:225], v[88:91]
	v_mfma_f32_16x16x32_bf16 v[76:79], v[132:135], v[230:233], v[76:79]
	v_mfma_f32_16x16x32_bf16 v[72:75], v[178:181], v[230:233], v[72:75]
	s_setprio 0
	s_setprio 1
	v_mfma_f32_16x16x32_bf16 v[116:119], v[182:185], v[198:201], v[116:119]
	v_mfma_f32_16x16x32_bf16 v[112:115], v[190:193], v[198:201], v[112:115]
	v_mfma_f32_16x16x32_bf16 v[100:103], v[182:185], v[210:213], v[100:103]
	v_mfma_f32_16x16x32_bf16 v[96:99], v[190:193], v[210:213], v[96:99]
	v_mfma_f32_16x16x32_bf16 v[84:87], v[182:185], v[218:221], v[84:87]
	v_mfma_f32_16x16x32_bf16 v[80:83], v[190:193], v[218:221], v[80:83]
	v_mfma_f32_16x16x32_bf16 v[68:71], v[182:185], v[226:229], v[68:71]
	v_mfma_f32_16x16x32_bf16 v[64:67], v[190:193], v[226:229], v[64:67]
	v_mfma_f32_16x16x32_bf16 v[116:119], v[186:189], v[206:209], v[116:119]
	v_mfma_f32_16x16x32_bf16 v[112:115], v[194:197], v[206:209], v[112:115]
	v_mfma_f32_16x16x32_bf16 v[100:103], v[186:189], v[214:217], v[100:103]
	v_mfma_f32_16x16x32_bf16 v[96:99], v[194:197], v[214:217], v[96:99]
	v_mfma_f32_16x16x32_bf16 v[84:87], v[186:189], v[222:225], v[84:87]
	v_mfma_f32_16x16x32_bf16 v[80:83], v[194:197], v[222:225], v[80:83]
	v_mfma_f32_16x16x32_bf16 v[68:71], v[186:189], v[230:233], v[68:71]
	v_mfma_f32_16x16x32_bf16 v[64:67], v[194:197], v[230:233], v[64:67]
	s_setprio 0
	s_barrier
	s_add_i32 s57, s47, s38
	v_lshl_add_u64 v[202:203], s[28:29], 0, v[140:141]
	s_mov_b32 m0, s57
	ds_read_b128 v[198:201], v176 offset:16384
	ds_read_b128 v[206:209], v176 offset:17408
	ds_read_b128 v[210:213], v176 offset:18432
	ds_read_b128 v[214:217], v176 offset:19456
	ds_read_b128 v[218:221], v176 offset:20480
	ds_read_b128 v[222:225], v176 offset:21504
	ds_read_b128 v[226:229], v176 offset:22528
	ds_read_b128 v[230:233], v176 offset:23552
	global_load_lds_dwordx4 v140, s[28:29]
	s_add_i32 m0, s57, 0x2000
	s_add_u32 s58, s28, 0x40000
	v_lshl_add_u64 v[234:235], s[28:29], 0, v[142:143]
	s_addc_u32 s59, s29, 0
	s_add_i32 s57, s48, s38
	global_load_lds_dwordx4 v142, s[28:29]
	s_mov_b32 m0, s57
	v_lshl_add_u64 v[238:239], s[30:31], 0, v[138:139]
	global_load_lds_dwordx4 v140, s[58:59]
	s_add_i32 m0, s57, 0x2000
	s_nop 0
	global_load_lds_dwordx4 v142, s[58:59]
	v_lshl_add_u64 v[236:237], s[30:31], 0, v[136:137]
	s_mov_b32 m0, s7
	s_nop 0
	global_load_lds_dwordx4 v136, s[30:31]
	s_mov_b32 m0, s39
	s_nop 0
	global_load_lds_dwordx4 v138, s[30:31]
	s_waitcnt vmcnt(8)
	s_waitcnt lgkmcnt(0)
	s_barrier
	s_setprio 1
	s_waitcnt lgkmcnt(0)
	v_mfma_f32_16x16x32_bf16 v[60:63], v[128:131], v[198:201], v[60:63]
	v_mfma_f32_16x16x32_bf16 v[56:59], v[158:161], v[198:201], v[56:59]
	v_mfma_f32_16x16x32_bf16 v[44:47], v[128:131], v[210:213], v[44:47]
	v_mfma_f32_16x16x32_bf16 v[40:43], v[158:161], v[210:213], v[40:43]
	v_mfma_f32_16x16x32_bf16 v[28:31], v[128:131], v[218:221], v[28:31]
	v_mfma_f32_16x16x32_bf16 v[24:27], v[158:161], v[218:221], v[24:27]
	v_mfma_f32_16x16x32_bf16 v[12:15], v[128:131], v[226:229], v[12:15]
	v_mfma_f32_16x16x32_bf16 v[8:11], v[158:161], v[226:229], v[8:11]
	v_mfma_f32_16x16x32_bf16 v[60:63], v[132:135], v[206:209], v[60:63]
	v_mfma_f32_16x16x32_bf16 v[56:59], v[178:181], v[206:209], v[56:59]
	v_mfma_f32_16x16x32_bf16 v[44:47], v[132:135], v[214:217], v[44:47]
	v_mfma_f32_16x16x32_bf16 v[40:43], v[178:181], v[214:217], v[40:43]
	v_mfma_f32_16x16x32_bf16 v[28:31], v[132:135], v[222:225], v[28:31]
	v_mfma_f32_16x16x32_bf16 v[24:27], v[178:181], v[222:225], v[24:27]
	v_mfma_f32_16x16x32_bf16 v[12:15], v[132:135], v[230:233], v[12:15]
	v_mfma_f32_16x16x32_bf16 v[8:11], v[178:181], v[230:233], v[8:11]
	s_setprio 0
	s_setprio 1
	v_mfma_f32_16x16x32_bf16 v[52:55], v[182:185], v[198:201], v[52:55]
	v_mfma_f32_16x16x32_bf16 v[48:51], v[190:193], v[198:201], v[48:51]
	v_mfma_f32_16x16x32_bf16 v[36:39], v[182:185], v[210:213], v[36:39]
	v_mfma_f32_16x16x32_bf16 v[32:35], v[190:193], v[210:213], v[32:35]
	v_mfma_f32_16x16x32_bf16 v[20:23], v[182:185], v[218:221], v[20:23]
	v_mfma_f32_16x16x32_bf16 v[16:19], v[190:193], v[218:221], v[16:19]
	v_mfma_f32_16x16x32_bf16 v[4:7], v[182:185], v[226:229], v[4:7]
	v_mfma_f32_16x16x32_bf16 v[0:3], v[190:193], v[226:229], v[0:3]
	v_mfma_f32_16x16x32_bf16 v[52:55], v[186:189], v[206:209], v[52:55]
	v_mfma_f32_16x16x32_bf16 v[48:51], v[194:197], v[206:209], v[48:51]
	v_mfma_f32_16x16x32_bf16 v[36:39], v[186:189], v[214:217], v[36:39]
	v_mfma_f32_16x16x32_bf16 v[32:35], v[194:197], v[214:217], v[32:35]
	v_mfma_f32_16x16x32_bf16 v[20:23], v[186:189], v[222:225], v[20:23]
	v_mfma_f32_16x16x32_bf16 v[16:19], v[194:197], v[222:225], v[16:19]
	v_mfma_f32_16x16x32_bf16 v[4:7], v[186:189], v[230:233], v[4:7]
	v_mfma_f32_16x16x32_bf16 v[0:3], v[194:197], v[230:233], v[0:3]
	s_setprio 0
	s_barrier
	s_add_i32 s57, 0, 0x18000
	v_add_u32_e32 v144, s57, v170
	s_add_i32 s58, 0, 0x1c000
	ds_read_b128 v[128:131], v144
	ds_read_b128 v[132:135], v144 offset:1024
	ds_read_b128 v[158:161], v144 offset:2048
	ds_read_b128 v[178:181], v144 offset:3072
	v_add_u32_e32 v144, s58, v170
	ds_read_b128 v[182:185], v144
	ds_read_b128 v[186:189], v144 offset:1024
	ds_read_b128 v[190:193], v144 offset:2048
	ds_read_b128 v[194:197], v144 offset:3072
	s_add_u32 s30, s30, 0x40000
	s_addc_u32 s31, s31, 0
	s_mov_b32 m0, s40
	ds_read_b128 v[198:201], v176 offset:32768
	ds_read_b128 v[206:209], v176 offset:33792
	ds_read_b128 v[210:213], v176 offset:34816
	ds_read_b128 v[214:217], v176 offset:35840
	ds_read_b128 v[218:221], v176 offset:36864
	ds_read_b128 v[222:225], v176 offset:37888
	ds_read_b128 v[226:229], v176 offset:38912
	ds_read_b128 v[230:233], v176 offset:39936
	global_load_lds_dwordx4 v136, s[30:31]
	s_mov_b32 m0, s41
	s_nop 0
	global_load_lds_dwordx4 v138, s[30:31]
	s_waitcnt vmcnt(8)
	s_waitcnt lgkmcnt(0)
	s_barrier
	s_setprio 1
	s_waitcnt lgkmcnt(0)
	v_mfma_f32_16x16x32_bf16 v[124:127], v[128:131], v[198:201], v[124:127]
	v_mfma_f32_16x16x32_bf16 v[120:123], v[158:161], v[198:201], v[120:123]
	v_mfma_f32_16x16x32_bf16 v[108:111], v[128:131], v[210:213], v[108:111]
	v_mfma_f32_16x16x32_bf16 v[104:107], v[158:161], v[210:213], v[104:107]
	v_mfma_f32_16x16x32_bf16 v[92:95], v[128:131], v[218:221], v[92:95]
	v_mfma_f32_16x16x32_bf16 v[88:91], v[158:161], v[218:221], v[88:91]
	v_mfma_f32_16x16x32_bf16 v[76:79], v[128:131], v[226:229], v[76:79]
	v_mfma_f32_16x16x32_bf16 v[72:75], v[158:161], v[226:229], v[72:75]
	v_mfma_f32_16x16x32_bf16 v[124:127], v[132:135], v[206:209], v[124:127]
	v_mfma_f32_16x16x32_bf16 v[120:123], v[178:181], v[206:209], v[120:123]
	v_mfma_f32_16x16x32_bf16 v[108:111], v[132:135], v[214:217], v[108:111]
	v_mfma_f32_16x16x32_bf16 v[104:107], v[178:181], v[214:217], v[104:107]
	v_mfma_f32_16x16x32_bf16 v[92:95], v[132:135], v[222:225], v[92:95]
	v_mfma_f32_16x16x32_bf16 v[88:91], v[178:181], v[222:225], v[88:91]
	v_mfma_f32_16x16x32_bf16 v[76:79], v[132:135], v[230:233], v[76:79]
	v_mfma_f32_16x16x32_bf16 v[72:75], v[178:181], v[230:233], v[72:75]
	s_setprio 0
	s_setprio 1
	v_mfma_f32_16x16x32_bf16 v[116:119], v[182:185], v[198:201], v[116:119]
	v_mfma_f32_16x16x32_bf16 v[112:115], v[190:193], v[198:201], v[112:115]
	v_mfma_f32_16x16x32_bf16 v[100:103], v[182:185], v[210:213], v[100:103]
	v_mfma_f32_16x16x32_bf16 v[96:99], v[190:193], v[210:213], v[96:99]
	v_mfma_f32_16x16x32_bf16 v[84:87], v[182:185], v[218:221], v[84:87]
	v_mfma_f32_16x16x32_bf16 v[80:83], v[190:193], v[218:221], v[80:83]
	v_mfma_f32_16x16x32_bf16 v[68:71], v[182:185], v[226:229], v[68:71]
	v_mfma_f32_16x16x32_bf16 v[64:67], v[190:193], v[226:229], v[64:67]
	v_mfma_f32_16x16x32_bf16 v[116:119], v[186:189], v[206:209], v[116:119]
	v_mfma_f32_16x16x32_bf16 v[112:115], v[194:197], v[206:209], v[112:115]
	v_mfma_f32_16x16x32_bf16 v[100:103], v[186:189], v[214:217], v[100:103]
	v_mfma_f32_16x16x32_bf16 v[96:99], v[194:197], v[214:217], v[96:99]
	v_mfma_f32_16x16x32_bf16 v[84:87], v[186:189], v[222:225], v[84:87]
	v_mfma_f32_16x16x32_bf16 v[80:83], v[194:197], v[222:225], v[80:83]
	v_mfma_f32_16x16x32_bf16 v[68:71], v[186:189], v[230:233], v[68:71]
	v_mfma_f32_16x16x32_bf16 v[64:67], v[194:197], v[230:233], v[64:67]
	s_setprio 0
	s_barrier
	s_add_i32 s30, s57, s38
	v_lshl_add_u64 v[202:203], v[202:203], 0, s[14:15]
	s_mov_b32 m0, s30
	ds_read_b128 v[198:201], v176 offset:49152
	ds_read_b128 v[206:209], v176 offset:50176
	ds_read_b128 v[210:213], v176 offset:51200
	ds_read_b128 v[214:217], v176 offset:52224
	ds_read_b128 v[218:221], v176 offset:53248
	ds_read_b128 v[222:225], v176 offset:54272
	ds_read_b128 v[226:229], v176 offset:55296
	ds_read_b128 v[230:233], v176 offset:56320
	global_load_lds_dwordx4 v[202:203], off
	s_add_i32 m0, s30, 0x2000
	s_add_u32 s28, s28, 0x40080
	v_lshl_add_u64 v[202:203], v[234:235], 0, s[14:15]
	s_addc_u32 s29, s29, 0
	s_add_i32 s30, s58, s38
	global_load_lds_dwordx4 v[202:203], off
	s_mov_b32 m0, s30
	s_nop 0
	global_load_lds_dwordx4 v140, s[28:29]
	s_add_i32 m0, s30, 0x2000
	s_nop 0
	global_load_lds_dwordx4 v142, s[28:29]
	v_lshl_add_u64 v[202:203], v[236:237], 0, s[14:15]
	s_mov_b32 m0, s43
	s_nop 0
	global_load_lds_dwordx4 v[202:203], off
	v_lshl_add_u64 v[202:203], v[238:239], 0, s[14:15]
	s_mov_b32 m0, s44
	s_nop 0
	global_load_lds_dwordx4 v[202:203], off
	s_waitcnt vmcnt(8)
	s_waitcnt lgkmcnt(0)
	s_barrier
	s_setprio 1
	s_waitcnt lgkmcnt(0)
	v_mfma_f32_16x16x32_bf16 v[60:63], v[128:131], v[198:201], v[60:63]
	v_mfma_f32_16x16x32_bf16 v[56:59], v[158:161], v[198:201], v[56:59]
	v_mfma_f32_16x16x32_bf16 v[44:47], v[128:131], v[210:213], v[44:47]
	v_mfma_f32_16x16x32_bf16 v[40:43], v[158:161], v[210:213], v[40:43]
	v_mfma_f32_16x16x32_bf16 v[28:31], v[128:131], v[218:221], v[28:31]
	v_mfma_f32_16x16x32_bf16 v[24:27], v[158:161], v[218:221], v[24:27]
	v_mfma_f32_16x16x32_bf16 v[12:15], v[128:131], v[226:229], v[12:15]
	v_mfma_f32_16x16x32_bf16 v[8:11], v[158:161], v[226:229], v[8:11]
	v_mfma_f32_16x16x32_bf16 v[60:63], v[132:135], v[206:209], v[60:63]
	v_mfma_f32_16x16x32_bf16 v[56:59], v[178:181], v[206:209], v[56:59]
	v_mfma_f32_16x16x32_bf16 v[44:47], v[132:135], v[214:217], v[44:47]
	v_mfma_f32_16x16x32_bf16 v[40:43], v[178:181], v[214:217], v[40:43]
	v_mfma_f32_16x16x32_bf16 v[28:31], v[132:135], v[222:225], v[28:31]
	v_mfma_f32_16x16x32_bf16 v[24:27], v[178:181], v[222:225], v[24:27]
	v_mfma_f32_16x16x32_bf16 v[12:15], v[132:135], v[230:233], v[12:15]
	v_mfma_f32_16x16x32_bf16 v[8:11], v[178:181], v[230:233], v[8:11]
	s_setprio 0
	s_setprio 1
	v_mfma_f32_16x16x32_bf16 v[52:55], v[182:185], v[198:201], v[52:55]
	v_mfma_f32_16x16x32_bf16 v[48:51], v[190:193], v[198:201], v[48:51]
	v_mfma_f32_16x16x32_bf16 v[36:39], v[182:185], v[210:213], v[36:39]
	v_mfma_f32_16x16x32_bf16 v[32:35], v[190:193], v[210:213], v[32:35]
	v_mfma_f32_16x16x32_bf16 v[20:23], v[182:185], v[218:221], v[20:23]
	v_mfma_f32_16x16x32_bf16 v[16:19], v[190:193], v[218:221], v[16:19]
	v_mfma_f32_16x16x32_bf16 v[4:7], v[182:185], v[226:229], v[4:7]
	v_mfma_f32_16x16x32_bf16 v[0:3], v[190:193], v[226:229], v[0:3]
	v_mfma_f32_16x16x32_bf16 v[52:55], v[186:189], v[206:209], v[52:55]
	v_mfma_f32_16x16x32_bf16 v[48:51], v[194:197], v[206:209], v[48:51]
	v_mfma_f32_16x16x32_bf16 v[36:39], v[186:189], v[214:217], v[36:39]
	v_mfma_f32_16x16x32_bf16 v[32:35], v[194:197], v[214:217], v[32:35]
	v_mfma_f32_16x16x32_bf16 v[20:23], v[186:189], v[222:225], v[20:23]
	v_mfma_f32_16x16x32_bf16 v[16:19], v[194:197], v[222:225], v[16:19]
	v_mfma_f32_16x16x32_bf16 v[4:7], v[186:189], v[230:233], v[4:7]
	v_mfma_f32_16x16x32_bf16 v[0:3], v[194:197], v[230:233], v[0:3]
	s_setprio 0
	s_barrier
	s_add_i32 s56, s56, 2
	s_add_u32 s26, s26, 0x100
	s_addc_u32 s27, s27, 0
	s_add_u32 s54, s54, 0x100
	s_addc_u32 s55, s55, 0
	s_cmp_gt_u32 s56, 13
	s_cbranch_scc0 .LBB0_335
	s_and_b64 vcc, exec, s[16:17]
	s_cbranch_vccz .LBB0_338
	s_barrier

.Llsb_skip_3:
.LBB0_791:
	ds_read_b128 v[44:47], v200
	ds_read_b128 v[52:55], v200 offset:1024
	ds_read_b128 v[112:115], v200 offset:2048
	ds_read_b128 v[124:127], v200 offset:3072
	ds_read_b128 v[136:139], v201
	ds_read_b128 v[148:151], v201 offset:1024
	ds_read_b128 v[152:155], v201 offset:2048
	ds_read_b128 v[156:159], v201 offset:3072
	s_add_u32 s24, s22, 0xfffd8080
	s_addc_u32 s25, s23, -1
	s_cmp_eq_u32 s56, 6
	s_cselect_b32 s27, s19, s25
	s_cselect_b32 s26, s18, s24
	s_cselect_b32 s25, s21, s55
	s_cselect_b32 s24, s20, s54
	s_mov_b32 m0, s39
	ds_read_b128 v[160:163], v202
	ds_read_b128 v[208:211], v202 offset:1024
	ds_read_b128 v[212:215], v202 offset:2048
	ds_read_b128 v[216:219], v202 offset:3072
	ds_read_b128 v[220:223], v202 offset:4096
	ds_read_b128 v[224:227], v202 offset:5120
	ds_read_b128 v[228:231], v202 offset:6144
	ds_read_b128 v[232:235], v202 offset:7168
	global_load_lds_dwordx4 v178, s[22:23]
	s_mov_b32 m0, s40
	s_nop 0
	global_load_lds_dwordx4 v180, s[22:23]
	s_waitcnt vmcnt(8)
	s_waitcnt lgkmcnt(0)
	s_barrier
	s_setprio 1
	s_waitcnt lgkmcnt(0)
	v_mfma_f32_16x16x32_bf16 v[144:147], v[44:47], v[160:163], v[144:147]
	v_mfma_f32_16x16x32_bf16 v[140:143], v[112:115], v[160:163], v[140:143]
	v_mfma_f32_16x16x32_bf16 v[120:123], v[44:47], v[212:215], v[120:123]
	v_mfma_f32_16x16x32_bf16 v[116:119], v[112:115], v[212:215], v[116:119]
	v_mfma_f32_16x16x32_bf16 v[100:103], v[44:47], v[220:223], v[100:103]
	v_mfma_f32_16x16x32_bf16 v[96:99], v[112:115], v[220:223], v[96:99]
	v_mfma_f32_16x16x32_bf16 v[84:87], v[44:47], v[228:231], v[84:87]
	v_mfma_f32_16x16x32_bf16 v[80:83], v[112:115], v[228:231], v[80:83]
	v_mfma_f32_16x16x32_bf16 v[144:147], v[52:55], v[208:211], v[144:147]
	v_mfma_f32_16x16x32_bf16 v[140:143], v[124:127], v[208:211], v[140:143]
	v_mfma_f32_16x16x32_bf16 v[120:123], v[52:55], v[216:219], v[120:123]
	v_mfma_f32_16x16x32_bf16 v[116:119], v[124:127], v[216:219], v[116:119]
	v_mfma_f32_16x16x32_bf16 v[100:103], v[52:55], v[224:227], v[100:103]
	v_mfma_f32_16x16x32_bf16 v[96:99], v[124:127], v[224:227], v[96:99]
	v_mfma_f32_16x16x32_bf16 v[84:87], v[52:55], v[232:235], v[84:87]
	v_mfma_f32_16x16x32_bf16 v[80:83], v[124:127], v[232:235], v[80:83]
	s_setprio 0
	s_setprio 1
	v_mfma_f32_16x16x32_bf16 v[132:135], v[136:139], v[160:163], v[132:135]
	v_mfma_f32_16x16x32_bf16 v[128:131], v[152:155], v[160:163], v[128:131]
	v_mfma_f32_16x16x32_bf16 v[108:111], v[136:139], v[212:215], v[108:111]
	v_mfma_f32_16x16x32_bf16 v[104:107], v[152:155], v[212:215], v[104:107]
	v_mfma_f32_16x16x32_bf16 v[92:95], v[136:139], v[220:223], v[92:95]
	v_mfma_f32_16x16x32_bf16 v[88:91], v[152:155], v[220:223], v[88:91]
	v_mfma_f32_16x16x32_bf16 v[76:79], v[136:139], v[228:231], v[76:79]
	v_mfma_f32_16x16x32_bf16 v[72:75], v[152:155], v[228:231], v[72:75]
	v_mfma_f32_16x16x32_bf16 v[132:135], v[148:151], v[208:211], v[132:135]
	v_mfma_f32_16x16x32_bf16 v[128:131], v[156:159], v[208:211], v[128:131]
	v_mfma_f32_16x16x32_bf16 v[108:111], v[148:151], v[216:219], v[108:111]
	v_mfma_f32_16x16x32_bf16 v[104:107], v[156:159], v[216:219], v[104:107]
	v_mfma_f32_16x16x32_bf16 v[92:95], v[148:151], v[224:227], v[92:95]
	v_mfma_f32_16x16x32_bf16 v[88:91], v[156:159], v[224:227], v[88:91]
	v_mfma_f32_16x16x32_bf16 v[76:79], v[148:151], v[232:235], v[76:79]
	v_mfma_f32_16x16x32_bf16 v[72:75], v[156:159], v[232:235], v[72:75]
	s_setprio 0
	s_barrier
	s_mov_b32 m0, s41
	v_lshl_add_u64 v[236:237], s[24:25], 0, v[168:169]
	s_add_u32 s58, s24, 0x28000
	ds_read_b128 v[160:163], v202 offset:16384
	ds_read_b128 v[208:211], v202 offset:17408
	ds_read_b128 v[212:215], v202 offset:18432
	ds_read_b128 v[216:219], v202 offset:19456
	ds_read_b128 v[220:223], v202 offset:20480
	ds_read_b128 v[224:227], v202 offset:21504
	ds_read_b128 v[228:231], v202 offset:22528
	ds_read_b128 v[232:235], v202 offset:23552
	global_load_lds_dwordx4 v168, s[24:25]
	v_lshl_add_u64 v[238:239], s[24:25], 0, v[164:165]
	s_mov_b32 m0, s43
	s_addc_u32 s59, s25, 0
	global_load_lds_dwordx4 v164, s[24:25]
	s_mov_b32 m0, s44
	v_lshl_add_u64 v[242:243], s[26:27], 0, v[166:167]
	global_load_lds_dwordx4 v168, s[58:59]
	s_mov_b32 m0, s45
	s_nop 0
	global_load_lds_dwordx4 v164, s[58:59]
	v_lshl_add_u64 v[240:241], s[26:27], 0, v[170:171]
	s_mov_b32 m0, s30
	s_nop 0
	global_load_lds_dwordx4 v170, s[26:27]
	s_mov_b32 m0, s31
	s_nop 0
	global_load_lds_dwordx4 v166, s[26:27]
	s_waitcnt vmcnt(8)
	s_waitcnt lgkmcnt(0)
	s_barrier
	s_setprio 1
	s_waitcnt lgkmcnt(0)
	v_mfma_f32_16x16x32_bf16 v[68:71], v[44:47], v[160:163], v[68:71]
	v_mfma_f32_16x16x32_bf16 v[64:67], v[112:115], v[160:163], v[64:67]
	v_mfma_f32_16x16x32_bf16 v[48:51], v[44:47], v[212:215], v[48:51]
	v_mfma_f32_16x16x32_bf16 v[40:43], v[112:115], v[212:215], v[40:43]
	v_mfma_f32_16x16x32_bf16 v[28:31], v[44:47], v[220:223], v[28:31]
	v_mfma_f32_16x16x32_bf16 v[24:27], v[112:115], v[220:223], v[24:27]
	v_mfma_f32_16x16x32_bf16 v[12:15], v[44:47], v[228:231], v[12:15]
	v_mfma_f32_16x16x32_bf16 v[8:11], v[112:115], v[228:231], v[8:11]
	v_mfma_f32_16x16x32_bf16 v[68:71], v[52:55], v[208:211], v[68:71]
	v_mfma_f32_16x16x32_bf16 v[64:67], v[124:127], v[208:211], v[64:67]
	v_mfma_f32_16x16x32_bf16 v[48:51], v[52:55], v[216:219], v[48:51]
	v_mfma_f32_16x16x32_bf16 v[40:43], v[124:127], v[216:219], v[40:43]
	v_mfma_f32_16x16x32_bf16 v[28:31], v[52:55], v[224:227], v[28:31]
	v_mfma_f32_16x16x32_bf16 v[24:27], v[124:127], v[224:227], v[24:27]
	v_mfma_f32_16x16x32_bf16 v[12:15], v[52:55], v[232:235], v[12:15]
	v_mfma_f32_16x16x32_bf16 v[8:11], v[124:127], v[232:235], v[8:11]
	s_setprio 0
	s_setprio 1
	v_mfma_f32_16x16x32_bf16 v[36:39], v[136:139], v[212:215], v[36:39]
	v_mfma_f32_16x16x32_bf16 v[32:35], v[152:155], v[212:215], v[32:35]
	v_mfma_f32_16x16x32_bf16 v[20:23], v[136:139], v[220:223], v[20:23]
	v_mfma_f32_16x16x32_bf16 v[16:19], v[152:155], v[220:223], v[16:19]
	v_mfma_f32_16x16x32_bf16 v[4:7], v[136:139], v[228:231], v[4:7]
	v_mfma_f32_16x16x32_bf16 v[0:3], v[152:155], v[228:231], v[0:3]
	v_mfma_f32_16x16x32_bf16 v[44:47], v[136:139], v[160:163], v[60:63]
	v_mfma_f32_16x16x32_bf16 v[52:55], v[152:155], v[160:163], v[56:59]
	v_mfma_f32_16x16x32_bf16 v[36:39], v[148:151], v[216:219], v[36:39]
	v_mfma_f32_16x16x32_bf16 v[32:35], v[156:159], v[216:219], v[32:35]
	v_mfma_f32_16x16x32_bf16 v[20:23], v[148:151], v[224:227], v[20:23]
	v_mfma_f32_16x16x32_bf16 v[16:19], v[156:159], v[224:227], v[16:19]
	v_mfma_f32_16x16x32_bf16 v[4:7], v[148:151], v[232:235], v[4:7]
	v_mfma_f32_16x16x32_bf16 v[0:3], v[156:159], v[232:235], v[0:3]
	v_mfma_f32_16x16x32_bf16 v[44:47], v[148:151], v[208:211], v[44:47]
	v_mfma_f32_16x16x32_bf16 v[52:55], v[156:159], v[208:211], v[52:55]
	s_setprio 0
	s_barrier
	ds_read_b128 v[56:59], v203
	ds_read_b128 v[60:63], v203 offset:1024
	ds_read_b128 v[112:115], v203 offset:2048
	ds_read_b128 v[124:127], v203 offset:3072
	ds_read_b128 v[136:139], v205
	ds_read_b128 v[148:151], v205 offset:1024
	ds_read_b128 v[152:155], v205 offset:2048
	ds_read_b128 v[156:159], v205 offset:3072
	s_add_u32 s26, s26, 0x28000
	s_addc_u32 s27, s27, 0
	s_mov_b32 m0, s33
	ds_read_b128 v[160:163], v202 offset:32768
	ds_read_b128 v[208:211], v202 offset:33792
	ds_read_b128 v[212:215], v202 offset:34816
	ds_read_b128 v[216:219], v202 offset:35840
	ds_read_b128 v[220:223], v202 offset:36864
	ds_read_b128 v[224:227], v202 offset:37888
	ds_read_b128 v[228:231], v202 offset:38912
	ds_read_b128 v[232:235], v202 offset:39936
	global_load_lds_dwordx4 v170, s[26:27]
	s_mov_b32 m0, s34
	s_nop 0
	global_load_lds_dwordx4 v166, s[26:27]
	s_waitcnt vmcnt(8)
	s_waitcnt lgkmcnt(0)
	s_barrier
	s_setprio 1
	s_waitcnt lgkmcnt(0)
	v_mfma_f32_16x16x32_bf16 v[144:147], v[56:59], v[160:163], v[144:147]
	v_mfma_f32_16x16x32_bf16 v[140:143], v[112:115], v[160:163], v[140:143]
	v_mfma_f32_16x16x32_bf16 v[120:123], v[56:59], v[212:215], v[120:123]
	v_mfma_f32_16x16x32_bf16 v[116:119], v[112:115], v[212:215], v[116:119]
	v_mfma_f32_16x16x32_bf16 v[100:103], v[56:59], v[220:223], v[100:103]
	v_mfma_f32_16x16x32_bf16 v[96:99], v[112:115], v[220:223], v[96:99]
	v_mfma_f32_16x16x32_bf16 v[84:87], v[56:59], v[228:231], v[84:87]
	v_mfma_f32_16x16x32_bf16 v[80:83], v[112:115], v[228:231], v[80:83]
	v_mfma_f32_16x16x32_bf16 v[144:147], v[60:63], v[208:211], v[144:147]
	v_mfma_f32_16x16x32_bf16 v[140:143], v[124:127], v[208:211], v[140:143]
	v_mfma_f32_16x16x32_bf16 v[120:123], v[60:63], v[216:219], v[120:123]
	v_mfma_f32_16x16x32_bf16 v[116:119], v[124:127], v[216:219], v[116:119]
	v_mfma_f32_16x16x32_bf16 v[100:103], v[60:63], v[224:227], v[100:103]
	v_mfma_f32_16x16x32_bf16 v[96:99], v[124:127], v[224:227], v[96:99]
	v_mfma_f32_16x16x32_bf16 v[84:87], v[60:63], v[232:235], v[84:87]
	v_mfma_f32_16x16x32_bf16 v[80:83], v[124:127], v[232:235], v[80:83]
	s_setprio 0
	s_setprio 1
	v_mfma_f32_16x16x32_bf16 v[132:135], v[136:139], v[160:163], v[132:135]
	v_mfma_f32_16x16x32_bf16 v[128:131], v[152:155], v[160:163], v[128:131]
	v_mfma_f32_16x16x32_bf16 v[108:111], v[136:139], v[212:215], v[108:111]
	v_mfma_f32_16x16x32_bf16 v[104:107], v[152:155], v[212:215], v[104:107]
	v_mfma_f32_16x16x32_bf16 v[92:95], v[136:139], v[220:223], v[92:95]
	v_mfma_f32_16x16x32_bf16 v[88:91], v[152:155], v[220:223], v[88:91]
	v_mfma_f32_16x16x32_bf16 v[76:79], v[136:139], v[228:231], v[76:79]
	v_mfma_f32_16x16x32_bf16 v[72:75], v[152:155], v[228:231], v[72:75]
	v_mfma_f32_16x16x32_bf16 v[132:135], v[148:151], v[208:211], v[132:135]
	v_mfma_f32_16x16x32_bf16 v[128:131], v[156:159], v[208:211], v[128:131]
	v_mfma_f32_16x16x32_bf16 v[108:111], v[148:151], v[216:219], v[108:111]
	v_mfma_f32_16x16x32_bf16 v[104:107], v[156:159], v[216:219], v[104:107]
	v_mfma_f32_16x16x32_bf16 v[92:95], v[148:151], v[224:227], v[92:95]
	v_mfma_f32_16x16x32_bf16 v[88:91], v[156:159], v[224:227], v[88:91]
	v_mfma_f32_16x16x32_bf16 v[76:79], v[148:151], v[232:235], v[76:79]
	v_mfma_f32_16x16x32_bf16 v[72:75], v[156:159], v[232:235], v[72:75]
	s_setprio 0
	s_barrier
	s_mov_b32 m0, s46
	v_lshl_add_u64 v[236:237], v[236:237], 0, s[14:15]
	s_add_u32 s24, s24, 0x28080
	ds_read_b128 v[160:163], v202 offset:49152
	ds_read_b128 v[208:211], v202 offset:50176
	ds_read_b128 v[212:215], v202 offset:51200
	ds_read_b128 v[216:219], v202 offset:52224
	ds_read_b128 v[220:223], v202 offset:53248
	ds_read_b128 v[224:227], v202 offset:54272
	ds_read_b128 v[228:231], v202 offset:55296
	ds_read_b128 v[232:235], v202 offset:56320
	global_load_lds_dwordx4 v[236:237], off
	v_lshl_add_u64 v[236:237], v[238:239], 0, s[14:15]
	s_mov_b32 m0, s47
	s_addc_u32 s25, s25, 0
	global_load_lds_dwordx4 v[236:237], off
	s_mov_b32 m0, s48
	s_nop 0
	global_load_lds_dwordx4 v168, s[24:25]
	s_mov_b32 m0, s49
	s_nop 0
	global_load_lds_dwordx4 v164, s[24:25]
	v_lshl_add_u64 v[236:237], v[240:241], 0, s[14:15]
	s_mov_b32 m0, s37
	s_nop 0
	global_load_lds_dwordx4 v[236:237], off
	v_lshl_add_u64 v[236:237], v[242:243], 0, s[14:15]
	s_mov_b32 m0, s38
	s_nop 0
	global_load_lds_dwordx4 v[236:237], off
	s_waitcnt vmcnt(8)
	s_waitcnt lgkmcnt(0)
	s_barrier
	s_setprio 1
	s_waitcnt lgkmcnt(0)
	v_mfma_f32_16x16x32_bf16 v[68:71], v[56:59], v[160:163], v[68:71]
	v_mfma_f32_16x16x32_bf16 v[64:67], v[112:115], v[160:163], v[64:67]
	v_mfma_f32_16x16x32_bf16 v[48:51], v[56:59], v[212:215], v[48:51]
	v_mfma_f32_16x16x32_bf16 v[40:43], v[112:115], v[212:215], v[40:43]
	v_mfma_f32_16x16x32_bf16 v[28:31], v[56:59], v[220:223], v[28:31]
	v_mfma_f32_16x16x32_bf16 v[24:27], v[112:115], v[220:223], v[24:27]
	v_mfma_f32_16x16x32_bf16 v[12:15], v[56:59], v[228:231], v[12:15]
	v_mfma_f32_16x16x32_bf16 v[8:11], v[112:115], v[228:231], v[8:11]
	v_mfma_f32_16x16x32_bf16 v[68:71], v[60:63], v[208:211], v[68:71]
	v_mfma_f32_16x16x32_bf16 v[64:67], v[124:127], v[208:211], v[64:67]
	v_mfma_f32_16x16x32_bf16 v[48:51], v[60:63], v[216:219], v[48:51]
	v_mfma_f32_16x16x32_bf16 v[40:43], v[124:127], v[216:219], v[40:43]
	v_mfma_f32_16x16x32_bf16 v[28:31], v[60:63], v[224:227], v[28:31]
	v_mfma_f32_16x16x32_bf16 v[24:27], v[124:127], v[224:227], v[24:27]
	v_mfma_f32_16x16x32_bf16 v[12:15], v[60:63], v[232:235], v[12:15]
	v_mfma_f32_16x16x32_bf16 v[8:11], v[124:127], v[232:235], v[8:11]
	s_setprio 0
	s_setprio 1
	v_mfma_f32_16x16x32_bf16 v[44:47], v[136:139], v[160:163], v[44:47]
	v_mfma_f32_16x16x32_bf16 v[60:63], v[148:151], v[208:211], v[44:47]
	v_mfma_f32_16x16x32_bf16 v[44:47], v[152:155], v[160:163], v[52:55]
	v_mfma_f32_16x16x32_bf16 v[36:39], v[136:139], v[212:215], v[36:39]
	v_mfma_f32_16x16x32_bf16 v[32:35], v[152:155], v[212:215], v[32:35]
	v_mfma_f32_16x16x32_bf16 v[20:23], v[136:139], v[220:223], v[20:23]
	v_mfma_f32_16x16x32_bf16 v[16:19], v[152:155], v[220:223], v[16:19]
	v_mfma_f32_16x16x32_bf16 v[4:7], v[136:139], v[228:231], v[4:7]
	v_mfma_f32_16x16x32_bf16 v[0:3], v[152:155], v[228:231], v[0:3]
	v_mfma_f32_16x16x32_bf16 v[56:59], v[156:159], v[208:211], v[44:47]
	v_mfma_f32_16x16x32_bf16 v[36:39], v[148:151], v[216:219], v[36:39]
	v_mfma_f32_16x16x32_bf16 v[32:35], v[156:159], v[216:219], v[32:35]
	v_mfma_f32_16x16x32_bf16 v[20:23], v[148:151], v[224:227], v[20:23]
	v_mfma_f32_16x16x32_bf16 v[16:19], v[156:159], v[224:227], v[16:19]
	v_mfma_f32_16x16x32_bf16 v[4:7], v[148:151], v[232:235], v[4:7]
	v_mfma_f32_16x16x32_bf16 v[0:3], v[156:159], v[232:235], v[0:3]
	s_setprio 0
	s_barrier
	s_add_i32 s56, s56, 2
	s_add_u32 s22, s22, 0x100
	s_addc_u32 s23, s23, 0
	s_add_u32 s54, s54, 0x100
	s_addc_u32 s55, s55, 0
	s_cmp_gt_u32 s56, 7
	s_cbranch_scc0 .LBB0_791
	s_and_b64 vcc, exec, s[16:17]
	s_cbranch_vccz .LBB0_794
	s_barrier

.Llsb_skip_5:
.LBB0_893:
	ds_read_b128 v[128:131], v189
	ds_read_b128 v[132:135], v189 offset:1024
	ds_read_b128 v[136:139], v189 offset:2048
	ds_read_b128 v[140:143], v189 offset:3072
	ds_read_b128 v[144:147], v190
	ds_read_b128 v[164:167], v190 offset:1024
	ds_read_b128 v[168:171], v190 offset:2048
	ds_read_b128 v[172:175], v190 offset:3072
	s_add_u32 s28, s26, 0xfffe0080
	s_addc_u32 s29, s27, -1
	s_cmp_eq_u32 s52, 4
	s_cselect_b32 s31, s19, s29
	s_cselect_b32 s30, s48, s28
	s_cselect_b32 s29, s17, s51
	s_cselect_b32 s28, s49, s50
	s_add_i32 m0, s25, 0xc000
	ds_read_b128 v[192:195], v191
	ds_read_b128 v[196:199], v191 offset:1024
	ds_read_b128 v[200:203], v191 offset:2048
	ds_read_b128 v[206:209], v191 offset:3072
	ds_read_b128 v[210:213], v191 offset:4096
	ds_read_b128 v[214:217], v191 offset:5120
	ds_read_b128 v[218:221], v191 offset:6144
	ds_read_b128 v[222:225], v191 offset:7168
	global_load_lds_dwordx4 v156, s[26:27]
	s_add_i32 m0, s25, 0xe000
	s_nop 0
	global_load_lds_dwordx4 v158, s[26:27]
	s_waitcnt vmcnt(8)
	s_waitcnt lgkmcnt(0)
	s_barrier
	s_setprio 1
	s_waitcnt lgkmcnt(0)
	v_mfma_f32_16x16x32_bf16 v[124:127], v[128:131], v[192:195], v[124:127]
	v_mfma_f32_16x16x32_bf16 v[120:123], v[136:139], v[192:195], v[120:123]
	v_mfma_f32_16x16x32_bf16 v[108:111], v[128:131], v[200:203], v[108:111]
	v_mfma_f32_16x16x32_bf16 v[104:107], v[136:139], v[200:203], v[104:107]
	v_mfma_f32_16x16x32_bf16 v[92:95], v[128:131], v[210:213], v[92:95]
	v_mfma_f32_16x16x32_bf16 v[88:91], v[136:139], v[210:213], v[88:91]
	v_mfma_f32_16x16x32_bf16 v[76:79], v[128:131], v[218:221], v[76:79]
	v_mfma_f32_16x16x32_bf16 v[72:75], v[136:139], v[218:221], v[72:75]
	v_mfma_f32_16x16x32_bf16 v[124:127], v[132:135], v[196:199], v[124:127]
	v_mfma_f32_16x16x32_bf16 v[120:123], v[140:143], v[196:199], v[120:123]
	v_mfma_f32_16x16x32_bf16 v[108:111], v[132:135], v[206:209], v[108:111]
	v_mfma_f32_16x16x32_bf16 v[104:107], v[140:143], v[206:209], v[104:107]
	v_mfma_f32_16x16x32_bf16 v[92:95], v[132:135], v[214:217], v[92:95]
	v_mfma_f32_16x16x32_bf16 v[88:91], v[140:143], v[214:217], v[88:91]
	v_mfma_f32_16x16x32_bf16 v[76:79], v[132:135], v[222:225], v[76:79]
	v_mfma_f32_16x16x32_bf16 v[72:75], v[140:143], v[222:225], v[72:75]
	s_setprio 0
	s_setprio 1
	v_mfma_f32_16x16x32_bf16 v[116:119], v[144:147], v[192:195], v[116:119]
	v_mfma_f32_16x16x32_bf16 v[112:115], v[168:171], v[192:195], v[112:115]
	v_mfma_f32_16x16x32_bf16 v[100:103], v[144:147], v[200:203], v[100:103]
	v_mfma_f32_16x16x32_bf16 v[96:99], v[168:171], v[200:203], v[96:99]
	v_mfma_f32_16x16x32_bf16 v[84:87], v[144:147], v[210:213], v[84:87]
	v_mfma_f32_16x16x32_bf16 v[80:83], v[168:171], v[210:213], v[80:83]
	v_mfma_f32_16x16x32_bf16 v[68:71], v[144:147], v[218:221], v[68:71]
	v_mfma_f32_16x16x32_bf16 v[64:67], v[168:171], v[218:221], v[64:67]
	v_mfma_f32_16x16x32_bf16 v[116:119], v[164:167], v[196:199], v[116:119]
	v_mfma_f32_16x16x32_bf16 v[112:115], v[172:175], v[196:199], v[112:115]
	v_mfma_f32_16x16x32_bf16 v[100:103], v[164:167], v[206:209], v[100:103]
	v_mfma_f32_16x16x32_bf16 v[96:99], v[172:175], v[206:209], v[96:99]
	v_mfma_f32_16x16x32_bf16 v[84:87], v[164:167], v[214:217], v[84:87]
	v_mfma_f32_16x16x32_bf16 v[80:83], v[172:175], v[214:217], v[80:83]
	v_mfma_f32_16x16x32_bf16 v[68:71], v[164:167], v[222:225], v[68:71]
	v_mfma_f32_16x16x32_bf16 v[64:67], v[172:175], v[222:225], v[64:67]
	s_setprio 0
	s_barrier
	s_add_i32 s53, s44, s36
	v_lshl_add_u64 v[226:227], s[28:29], 0, v[150:151]
	s_mov_b32 m0, s53
	ds_read_b128 v[192:195], v191 offset:16384
	ds_read_b128 v[196:199], v191 offset:17408
	ds_read_b128 v[200:203], v191 offset:18432
	ds_read_b128 v[206:209], v191 offset:19456
	ds_read_b128 v[210:213], v191 offset:20480
	ds_read_b128 v[214:217], v191 offset:21504
	ds_read_b128 v[218:221], v191 offset:22528
	ds_read_b128 v[222:225], v191 offset:23552
	global_load_lds_dwordx4 v150, s[28:29]
	s_add_i32 m0, s53, 0x2000
	s_add_u32 s54, s28, 0x20000
	v_lshl_add_u64 v[228:229], s[28:29], 0, v[154:155]
	s_addc_u32 s55, s29, 0
	s_add_i32 s53, s45, s36
	global_load_lds_dwordx4 v154, s[28:29]
	s_mov_b32 m0, s53
	v_lshl_add_u64 v[232:233], s[30:31], 0, v[152:153]
	global_load_lds_dwordx4 v150, s[54:55]
	s_add_i32 m0, s53, 0x2000
	s_nop 0
	global_load_lds_dwordx4 v154, s[54:55]
	v_lshl_add_u64 v[230:231], s[30:31], 0, v[148:149]
	s_mov_b32 m0, s25
	s_nop 0
	global_load_lds_dwordx4 v148, s[30:31]
	s_mov_b32 m0, s37
	s_nop 0
	global_load_lds_dwordx4 v152, s[30:31]
	s_waitcnt vmcnt(8)
	s_waitcnt lgkmcnt(0)
	s_barrier
	s_setprio 1
	s_waitcnt lgkmcnt(0)
	v_mfma_f32_16x16x32_bf16 v[60:63], v[128:131], v[192:195], v[60:63]
	v_mfma_f32_16x16x32_bf16 v[56:59], v[136:139], v[192:195], v[56:59]
	v_mfma_f32_16x16x32_bf16 v[44:47], v[128:131], v[200:203], v[44:47]
	v_mfma_f32_16x16x32_bf16 v[40:43], v[136:139], v[200:203], v[40:43]
	v_mfma_f32_16x16x32_bf16 v[28:31], v[128:131], v[210:213], v[28:31]
	v_mfma_f32_16x16x32_bf16 v[24:27], v[136:139], v[210:213], v[24:27]
	v_mfma_f32_16x16x32_bf16 v[12:15], v[128:131], v[218:221], v[12:15]
	v_mfma_f32_16x16x32_bf16 v[8:11], v[136:139], v[218:221], v[8:11]
	v_mfma_f32_16x16x32_bf16 v[60:63], v[132:135], v[196:199], v[60:63]
	v_mfma_f32_16x16x32_bf16 v[56:59], v[140:143], v[196:199], v[56:59]
	v_mfma_f32_16x16x32_bf16 v[44:47], v[132:135], v[206:209], v[44:47]
	v_mfma_f32_16x16x32_bf16 v[40:43], v[140:143], v[206:209], v[40:43]
	v_mfma_f32_16x16x32_bf16 v[28:31], v[132:135], v[214:217], v[28:31]
	v_mfma_f32_16x16x32_bf16 v[24:27], v[140:143], v[214:217], v[24:27]
	v_mfma_f32_16x16x32_bf16 v[12:15], v[132:135], v[222:225], v[12:15]
	v_mfma_f32_16x16x32_bf16 v[8:11], v[140:143], v[222:225], v[8:11]
	s_setprio 0
	s_setprio 1
	v_mfma_f32_16x16x32_bf16 v[52:55], v[144:147], v[192:195], v[52:55]
	v_mfma_f32_16x16x32_bf16 v[48:51], v[168:171], v[192:195], v[48:51]
	v_mfma_f32_16x16x32_bf16 v[36:39], v[144:147], v[200:203], v[36:39]
	v_mfma_f32_16x16x32_bf16 v[32:35], v[168:171], v[200:203], v[32:35]
	v_mfma_f32_16x16x32_bf16 v[20:23], v[144:147], v[210:213], v[20:23]
	v_mfma_f32_16x16x32_bf16 v[16:19], v[168:171], v[210:213], v[16:19]
	v_mfma_f32_16x16x32_bf16 v[4:7], v[144:147], v[218:221], v[4:7]
	v_mfma_f32_16x16x32_bf16 v[0:3], v[168:171], v[218:221], v[0:3]
	v_mfma_f32_16x16x32_bf16 v[52:55], v[164:167], v[196:199], v[52:55]
	v_mfma_f32_16x16x32_bf16 v[48:51], v[172:175], v[196:199], v[48:51]
	v_mfma_f32_16x16x32_bf16 v[36:39], v[164:167], v[206:209], v[36:39]
	v_mfma_f32_16x16x32_bf16 v[32:35], v[172:175], v[206:209], v[32:35]
	v_mfma_f32_16x16x32_bf16 v[20:23], v[164:167], v[214:217], v[20:23]
	v_mfma_f32_16x16x32_bf16 v[16:19], v[172:175], v[214:217], v[16:19]
	v_mfma_f32_16x16x32_bf16 v[4:7], v[164:167], v[222:225], v[4:7]
	v_mfma_f32_16x16x32_bf16 v[0:3], v[172:175], v[222:225], v[0:3]
	s_setprio 0
	s_barrier
	s_add_i32 s53, 0, 0x18000
	s_add_i32 s54, 0, 0x1c000
	v_add_u32_e32 v140, s53, v187
	v_add_u32_e32 v172, s54, v187
	ds_read_b128 v[128:131], v140
	ds_read_b128 v[132:135], v140 offset:1024
	ds_read_b128 v[136:139], v140 offset:2048
	ds_read_b128 v[140:143], v140 offset:3072
	ds_read_b128 v[144:147], v172
	ds_read_b128 v[164:167], v172 offset:1024
	ds_read_b128 v[168:171], v172 offset:2048
	ds_read_b128 v[172:175], v172 offset:3072
	s_add_u32 s30, s30, 0x20000
	s_addc_u32 s31, s31, 0
	s_mov_b32 m0, s38
	ds_read_b128 v[192:195], v191 offset:32768
	ds_read_b128 v[196:199], v191 offset:33792
	ds_read_b128 v[200:203], v191 offset:34816
	ds_read_b128 v[206:209], v191 offset:35840
	ds_read_b128 v[210:213], v191 offset:36864
	ds_read_b128 v[214:217], v191 offset:37888
	ds_read_b128 v[218:221], v191 offset:38912
	ds_read_b128 v[222:225], v191 offset:39936
	global_load_lds_dwordx4 v148, s[30:31]
	s_mov_b32 m0, s39
	s_nop 0
	global_load_lds_dwordx4 v152, s[30:31]
	s_waitcnt vmcnt(8)
	s_waitcnt lgkmcnt(0)
	s_barrier
	s_setprio 1
	s_waitcnt lgkmcnt(0)
	v_mfma_f32_16x16x32_bf16 v[124:127], v[128:131], v[192:195], v[124:127]
	v_mfma_f32_16x16x32_bf16 v[120:123], v[136:139], v[192:195], v[120:123]
	v_mfma_f32_16x16x32_bf16 v[108:111], v[128:131], v[200:203], v[108:111]
	v_mfma_f32_16x16x32_bf16 v[104:107], v[136:139], v[200:203], v[104:107]
	v_mfma_f32_16x16x32_bf16 v[92:95], v[128:131], v[210:213], v[92:95]
	v_mfma_f32_16x16x32_bf16 v[88:91], v[136:139], v[210:213], v[88:91]
	v_mfma_f32_16x16x32_bf16 v[76:79], v[128:131], v[218:221], v[76:79]
	v_mfma_f32_16x16x32_bf16 v[72:75], v[136:139], v[218:221], v[72:75]
	v_mfma_f32_16x16x32_bf16 v[124:127], v[132:135], v[196:199], v[124:127]
	v_mfma_f32_16x16x32_bf16 v[120:123], v[140:143], v[196:199], v[120:123]
	v_mfma_f32_16x16x32_bf16 v[108:111], v[132:135], v[206:209], v[108:111]
	v_mfma_f32_16x16x32_bf16 v[104:107], v[140:143], v[206:209], v[104:107]
	v_mfma_f32_16x16x32_bf16 v[92:95], v[132:135], v[214:217], v[92:95]
	v_mfma_f32_16x16x32_bf16 v[88:91], v[140:143], v[214:217], v[88:91]
	v_mfma_f32_16x16x32_bf16 v[76:79], v[132:135], v[222:225], v[76:79]
	v_mfma_f32_16x16x32_bf16 v[72:75], v[140:143], v[222:225], v[72:75]
	s_setprio 0
	s_setprio 1
	v_mfma_f32_16x16x32_bf16 v[116:119], v[144:147], v[192:195], v[116:119]
	v_mfma_f32_16x16x32_bf16 v[112:115], v[168:171], v[192:195], v[112:115]
	v_mfma_f32_16x16x32_bf16 v[100:103], v[144:147], v[200:203], v[100:103]
	v_mfma_f32_16x16x32_bf16 v[96:99], v[168:171], v[200:203], v[96:99]
	v_mfma_f32_16x16x32_bf16 v[84:87], v[144:147], v[210:213], v[84:87]
	v_mfma_f32_16x16x32_bf16 v[80:83], v[168:171], v[210:213], v[80:83]
	v_mfma_f32_16x16x32_bf16 v[68:71], v[144:147], v[218:221], v[68:71]
	v_mfma_f32_16x16x32_bf16 v[64:67], v[168:171], v[218:221], v[64:67]
	v_mfma_f32_16x16x32_bf16 v[116:119], v[164:167], v[196:199], v[116:119]
	v_mfma_f32_16x16x32_bf16 v[112:115], v[172:175], v[196:199], v[112:115]
	v_mfma_f32_16x16x32_bf16 v[100:103], v[164:167], v[206:209], v[100:103]
	v_mfma_f32_16x16x32_bf16 v[96:99], v[172:175], v[206:209], v[96:99]
	v_mfma_f32_16x16x32_bf16 v[84:87], v[164:167], v[214:217], v[84:87]
	v_mfma_f32_16x16x32_bf16 v[80:83], v[172:175], v[214:217], v[80:83]
	v_mfma_f32_16x16x32_bf16 v[68:71], v[164:167], v[222:225], v[68:71]
	v_mfma_f32_16x16x32_bf16 v[64:67], v[172:175], v[222:225], v[64:67]
	s_setprio 0
	s_barrier
	s_add_i32 s30, s53, s36
	v_lshl_add_u64 v[226:227], v[226:227], 0, s[12:13]
	s_mov_b32 m0, s30
	ds_read_b128 v[192:195], v191 offset:49152
	ds_read_b128 v[196:199], v191 offset:50176
	ds_read_b128 v[200:203], v191 offset:51200
	ds_read_b128 v[206:209], v191 offset:52224
	ds_read_b128 v[210:213], v191 offset:53248
	ds_read_b128 v[214:217], v191 offset:54272
	ds_read_b128 v[218:221], v191 offset:55296
	ds_read_b128 v[222:225], v191 offset:56320
	global_load_lds_dwordx4 v[226:227], off
	s_add_i32 m0, s30, 0x2000
	s_add_u32 s28, s28, 0x20080
	v_lshl_add_u64 v[226:227], v[228:229], 0, s[12:13]
	s_addc_u32 s29, s29, 0
	s_add_i32 s30, s54, s36
	global_load_lds_dwordx4 v[226:227], off
	s_mov_b32 m0, s30
	s_nop 0
	global_load_lds_dwordx4 v150, s[28:29]
	s_add_i32 m0, s30, 0x2000
	s_nop 0
	global_load_lds_dwordx4 v154, s[28:29]
	v_lshl_add_u64 v[226:227], v[230:231], 0, s[12:13]
	s_mov_b32 m0, s41
	s_nop 0
	global_load_lds_dwordx4 v[226:227], off
	v_lshl_add_u64 v[226:227], v[232:233], 0, s[12:13]
	s_mov_b32 m0, s42
	s_nop 0
	global_load_lds_dwordx4 v[226:227], off
	s_waitcnt vmcnt(8)
	s_waitcnt lgkmcnt(0)
	s_barrier
	s_setprio 1
	s_waitcnt lgkmcnt(0)
	v_mfma_f32_16x16x32_bf16 v[60:63], v[128:131], v[192:195], v[60:63]
	v_mfma_f32_16x16x32_bf16 v[56:59], v[136:139], v[192:195], v[56:59]
	v_mfma_f32_16x16x32_bf16 v[44:47], v[128:131], v[200:203], v[44:47]
	v_mfma_f32_16x16x32_bf16 v[40:43], v[136:139], v[200:203], v[40:43]
	v_mfma_f32_16x16x32_bf16 v[28:31], v[128:131], v[210:213], v[28:31]
	v_mfma_f32_16x16x32_bf16 v[24:27], v[136:139], v[210:213], v[24:27]
	v_mfma_f32_16x16x32_bf16 v[12:15], v[128:131], v[218:221], v[12:15]
	v_mfma_f32_16x16x32_bf16 v[8:11], v[136:139], v[218:221], v[8:11]
	v_mfma_f32_16x16x32_bf16 v[60:63], v[132:135], v[196:199], v[60:63]
	v_mfma_f32_16x16x32_bf16 v[56:59], v[140:143], v[196:199], v[56:59]
	v_mfma_f32_16x16x32_bf16 v[44:47], v[132:135], v[206:209], v[44:47]
	v_mfma_f32_16x16x32_bf16 v[40:43], v[140:143], v[206:209], v[40:43]
	v_mfma_f32_16x16x32_bf16 v[28:31], v[132:135], v[214:217], v[28:31]
	v_mfma_f32_16x16x32_bf16 v[24:27], v[140:143], v[214:217], v[24:27]
	v_mfma_f32_16x16x32_bf16 v[12:15], v[132:135], v[222:225], v[12:15]
	v_mfma_f32_16x16x32_bf16 v[8:11], v[140:143], v[222:225], v[8:11]
	s_setprio 0
	s_setprio 1
	v_mfma_f32_16x16x32_bf16 v[52:55], v[144:147], v[192:195], v[52:55]
	v_mfma_f32_16x16x32_bf16 v[48:51], v[168:171], v[192:195], v[48:51]
	v_mfma_f32_16x16x32_bf16 v[36:39], v[144:147], v[200:203], v[36:39]
	v_mfma_f32_16x16x32_bf16 v[32:35], v[168:171], v[200:203], v[32:35]
	v_mfma_f32_16x16x32_bf16 v[20:23], v[144:147], v[210:213], v[20:23]
	v_mfma_f32_16x16x32_bf16 v[16:19], v[168:171], v[210:213], v[16:19]
	v_mfma_f32_16x16x32_bf16 v[4:7], v[144:147], v[218:221], v[4:7]
	v_mfma_f32_16x16x32_bf16 v[0:3], v[168:171], v[218:221], v[0:3]
	v_mfma_f32_16x16x32_bf16 v[52:55], v[164:167], v[196:199], v[52:55]
	v_mfma_f32_16x16x32_bf16 v[48:51], v[172:175], v[196:199], v[48:51]
	v_mfma_f32_16x16x32_bf16 v[36:39], v[164:167], v[206:209], v[36:39]
	v_mfma_f32_16x16x32_bf16 v[32:35], v[172:175], v[206:209], v[32:35]
	v_mfma_f32_16x16x32_bf16 v[20:23], v[164:167], v[214:217], v[20:23]
	v_mfma_f32_16x16x32_bf16 v[16:19], v[172:175], v[214:217], v[16:19]
	v_mfma_f32_16x16x32_bf16 v[4:7], v[164:167], v[222:225], v[4:7]
	v_mfma_f32_16x16x32_bf16 v[0:3], v[172:175], v[222:225], v[0:3]
	s_setprio 0
	s_barrier
	s_add_i32 s52, s52, 2
	s_add_u32 s26, s26, 0x100
	s_addc_u32 s27, s27, 0
	s_add_u32 s50, s50, 0x100
	s_addc_u32 s51, s51, 0
	s_cmp_gt_u32 s52, 5
	s_cbranch_scc0 .LBB0_893
	s_and_b64 vcc, exec, s[14:15]
	s_cbranch_vccz .LBB0_896
	s_barrier

.Llsb_skip_8:
.LBB0_1088:
	ds_read_b128 v[128:131], v212
	ds_read_b128 v[132:135], v212 offset:1024
	ds_read_b128 v[136:139], v212 offset:2048
	ds_read_b128 v[140:143], v212 offset:3072
	ds_read_b128 v[144:147], v213
	ds_read_b128 v[148:151], v213 offset:1024
	ds_read_b128 v[152:155], v213 offset:2048
	ds_read_b128 v[156:159], v213 offset:3072
	s_add_u32 s22, s20, 0xfffc0080
	s_addc_u32 s23, s21, -1
	s_cmp_eq_u32 s54, 12
	s_cselect_b32 s25, s13, s23
	s_cselect_b32 s24, s50, s22
	s_cselect_b32 s23, s11, s53
	s_cselect_b32 s22, s51, s52
	v_lshl_add_u64 v[202:203], s[20:21], 0, v[182:183]
	s_add_i32 m0, s28, 0xc000
	ds_read_b128 v[160:163], v214
	ds_read_b128 v[164:167], v214 offset:1024
	ds_read_b128 v[168:171], v214 offset:2048
	ds_read_b128 v[172:175], v214 offset:3072
	ds_read_b128 v[190:193], v214 offset:4096
	ds_read_b128 v[194:197], v214 offset:5120
	ds_read_b128 v[198:201], v214 offset:6144
	ds_read_b128 v[216:219], v214 offset:7168
	global_load_lds_dwordx4 v182, s[20:21]
	v_lshl_add_u64 v[202:203], s[20:21], 0, v[184:185]
	s_add_i32 m0, s28, 0xe000
	s_nop 0
	global_load_lds_dwordx4 v184, s[20:21]
	s_waitcnt vmcnt(8)
	s_waitcnt lgkmcnt(0)
	s_barrier
	s_setprio 1
	s_waitcnt lgkmcnt(0)
	v_mfma_f32_16x16x32_bf16 v[124:127], v[128:131], v[160:163], v[124:127]
	v_mfma_f32_16x16x32_bf16 v[120:123], v[136:139], v[160:163], v[120:123]
	v_mfma_f32_16x16x32_bf16 v[112:115], v[128:131], v[168:171], v[112:115]
	v_mfma_f32_16x16x32_bf16 v[104:107], v[136:139], v[168:171], v[104:107]
	v_mfma_f32_16x16x32_bf16 v[96:99], v[128:131], v[190:193], v[96:99]
	v_mfma_f32_16x16x32_bf16 v[88:91], v[136:139], v[190:193], v[88:91]
	v_mfma_f32_16x16x32_bf16 v[84:87], v[128:131], v[198:201], v[84:87]
	v_mfma_f32_16x16x32_bf16 v[76:79], v[136:139], v[198:201], v[76:79]
	v_mfma_f32_16x16x32_bf16 v[124:127], v[132:135], v[164:167], v[124:127]
	v_mfma_f32_16x16x32_bf16 v[120:123], v[140:143], v[164:167], v[120:123]
	v_mfma_f32_16x16x32_bf16 v[112:115], v[132:135], v[172:175], v[112:115]
	v_mfma_f32_16x16x32_bf16 v[104:107], v[140:143], v[172:175], v[104:107]
	v_mfma_f32_16x16x32_bf16 v[96:99], v[132:135], v[194:197], v[96:99]
	v_mfma_f32_16x16x32_bf16 v[88:91], v[140:143], v[194:197], v[88:91]
	v_mfma_f32_16x16x32_bf16 v[84:87], v[132:135], v[216:219], v[84:87]
	v_mfma_f32_16x16x32_bf16 v[76:79], v[140:143], v[216:219], v[76:79]
	s_setprio 0
	s_setprio 1
	v_mfma_f32_16x16x32_bf16 v[116:119], v[144:147], v[160:163], v[116:119]
	v_mfma_f32_16x16x32_bf16 v[108:111], v[152:155], v[160:163], v[108:111]
	v_mfma_f32_16x16x32_bf16 v[100:103], v[144:147], v[168:171], v[100:103]
	v_mfma_f32_16x16x32_bf16 v[92:95], v[152:155], v[168:171], v[92:95]
	v_mfma_f32_16x16x32_bf16 v[80:83], v[144:147], v[190:193], v[80:83]
	v_mfma_f32_16x16x32_bf16 v[72:75], v[152:155], v[190:193], v[72:75]
	v_mfma_f32_16x16x32_bf16 v[68:71], v[144:147], v[198:201], v[68:71]
	v_mfma_f32_16x16x32_bf16 v[64:67], v[152:155], v[198:201], v[64:67]
	v_mfma_f32_16x16x32_bf16 v[116:119], v[148:151], v[164:167], v[116:119]
	v_mfma_f32_16x16x32_bf16 v[108:111], v[156:159], v[164:167], v[108:111]
	v_mfma_f32_16x16x32_bf16 v[100:103], v[148:151], v[172:175], v[100:103]
	v_mfma_f32_16x16x32_bf16 v[92:95], v[156:159], v[172:175], v[92:95]
	v_mfma_f32_16x16x32_bf16 v[80:83], v[148:151], v[194:197], v[80:83]
	v_mfma_f32_16x16x32_bf16 v[72:75], v[156:159], v[194:197], v[72:75]
	v_mfma_f32_16x16x32_bf16 v[68:71], v[148:151], v[216:219], v[68:71]
	v_mfma_f32_16x16x32_bf16 v[64:67], v[156:159], v[216:219], v[64:67]
	s_setprio 0
	s_barrier
	s_add_i32 s55, s43, s27
	v_lshl_add_u64 v[202:203], s[22:23], 0, v[176:177]
	s_mov_b32 m0, s55
	ds_read_b128 v[160:163], v214 offset:16384
	ds_read_b128 v[164:167], v214 offset:17408
	ds_read_b128 v[168:171], v214 offset:18432
	ds_read_b128 v[172:175], v214 offset:19456
	ds_read_b128 v[190:193], v214 offset:20480
	ds_read_b128 v[194:197], v214 offset:21504
	ds_read_b128 v[198:201], v214 offset:22528
	ds_read_b128 v[216:219], v214 offset:23552
	global_load_lds_dwordx4 v176, s[22:23]
	s_add_i32 m0, s55, 0x2000
	s_add_u32 s56, s22, 0x40000
	v_lshl_add_u64 v[220:221], s[22:23], 0, v[178:179]
	s_addc_u32 s57, s23, 0
	s_add_i32 s55, s44, s27
	global_load_lds_dwordx4 v178, s[22:23]
	s_mov_b32 m0, s55
	v_lshl_add_u64 v[224:225], s[24:25], 0, v[178:179]
	global_load_lds_dwordx4 v176, s[56:57]
	s_add_i32 m0, s55, 0x2000
	s_nop 0
	global_load_lds_dwordx4 v178, s[56:57]
	v_lshl_add_u64 v[222:223], s[24:25], 0, v[176:177]
	s_mov_b32 m0, s28
	s_nop 0
	global_load_lds_dwordx4 v176, s[24:25]
	s_mov_b32 m0, s29
	s_nop 0
	global_load_lds_dwordx4 v178, s[24:25]
	s_waitcnt vmcnt(8)
	s_waitcnt lgkmcnt(0)
	s_barrier
	s_setprio 1
	s_waitcnt lgkmcnt(0)
	v_mfma_f32_16x16x32_bf16 v[60:63], v[128:131], v[160:163], v[60:63]
	v_mfma_f32_16x16x32_bf16 v[56:59], v[136:139], v[160:163], v[56:59]
	v_mfma_f32_16x16x32_bf16 v[48:51], v[128:131], v[168:171], v[48:51]
	v_mfma_f32_16x16x32_bf16 v[40:43], v[136:139], v[168:171], v[40:43]
	v_mfma_f32_16x16x32_bf16 v[32:35], v[128:131], v[190:193], v[32:35]
	v_mfma_f32_16x16x32_bf16 v[24:27], v[136:139], v[190:193], v[24:27]
	v_mfma_f32_16x16x32_bf16 v[20:23], v[128:131], v[198:201], v[20:23]
	v_mfma_f32_16x16x32_bf16 v[12:15], v[136:139], v[198:201], v[12:15]
	v_mfma_f32_16x16x32_bf16 v[60:63], v[132:135], v[164:167], v[60:63]
	v_mfma_f32_16x16x32_bf16 v[56:59], v[140:143], v[164:167], v[56:59]
	v_mfma_f32_16x16x32_bf16 v[48:51], v[132:135], v[172:175], v[48:51]
	v_mfma_f32_16x16x32_bf16 v[40:43], v[140:143], v[172:175], v[40:43]
	v_mfma_f32_16x16x32_bf16 v[32:35], v[132:135], v[194:197], v[32:35]
	v_mfma_f32_16x16x32_bf16 v[24:27], v[140:143], v[194:197], v[24:27]
	v_mfma_f32_16x16x32_bf16 v[20:23], v[132:135], v[216:219], v[20:23]
	v_mfma_f32_16x16x32_bf16 v[12:15], v[140:143], v[216:219], v[12:15]
	s_setprio 0
	s_setprio 1
	v_mfma_f32_16x16x32_bf16 v[52:55], v[144:147], v[160:163], v[52:55]
	v_mfma_f32_16x16x32_bf16 v[44:47], v[152:155], v[160:163], v[44:47]
	v_mfma_f32_16x16x32_bf16 v[36:39], v[144:147], v[168:171], v[36:39]
	v_mfma_f32_16x16x32_bf16 v[28:31], v[152:155], v[168:171], v[28:31]
	v_mfma_f32_16x16x32_bf16 v[16:19], v[144:147], v[190:193], v[16:19]
	v_mfma_f32_16x16x32_bf16 v[8:11], v[152:155], v[190:193], v[8:11]
	v_mfma_f32_16x16x32_bf16 v[4:7], v[144:147], v[198:201], v[4:7]
	v_mfma_f32_16x16x32_bf16 v[0:3], v[152:155], v[198:201], v[0:3]
	v_mfma_f32_16x16x32_bf16 v[52:55], v[148:151], v[164:167], v[52:55]
	v_mfma_f32_16x16x32_bf16 v[44:47], v[156:159], v[164:167], v[44:47]
	v_mfma_f32_16x16x32_bf16 v[36:39], v[148:151], v[172:175], v[36:39]
	v_mfma_f32_16x16x32_bf16 v[28:31], v[156:159], v[172:175], v[28:31]
	v_mfma_f32_16x16x32_bf16 v[16:19], v[148:151], v[194:197], v[16:19]
	v_mfma_f32_16x16x32_bf16 v[8:11], v[156:159], v[194:197], v[8:11]
	v_mfma_f32_16x16x32_bf16 v[4:7], v[148:151], v[216:219], v[4:7]
	v_mfma_f32_16x16x32_bf16 v[0:3], v[156:159], v[216:219], v[0:3]
	s_setprio 0
	s_barrier
	s_add_i32 s55, 0, 0x18000
	s_add_i32 s56, 0, 0x1c000
	v_add_u32_e32 v140, s55, v210
	v_add_u32_e32 v156, s56, v210
	ds_read_b128 v[128:131], v140
	ds_read_b128 v[132:135], v140 offset:1024
	ds_read_b128 v[136:139], v140 offset:2048
	ds_read_b128 v[140:143], v140 offset:3072
	ds_read_b128 v[144:147], v156
	ds_read_b128 v[148:151], v156 offset:1024
	ds_read_b128 v[152:155], v156 offset:2048
	ds_read_b128 v[156:159], v156 offset:3072
	s_add_u32 s24, s24, 0x40000
	s_addc_u32 s25, s25, 0
	s_mov_b32 m0, s30
	ds_read_b128 v[160:163], v214 offset:32768
	ds_read_b128 v[164:167], v214 offset:33792
	ds_read_b128 v[168:171], v214 offset:34816
	ds_read_b128 v[172:175], v214 offset:35840
	ds_read_b128 v[190:193], v214 offset:36864
	ds_read_b128 v[194:197], v214 offset:37888
	ds_read_b128 v[198:201], v214 offset:38912
	ds_read_b128 v[216:219], v214 offset:39936
	global_load_lds_dwordx4 v176, s[24:25]
	s_mov_b32 m0, s31
	s_nop 0
	global_load_lds_dwordx4 v178, s[24:25]
	s_waitcnt vmcnt(8)
	s_waitcnt lgkmcnt(0)
	s_barrier
	s_setprio 1
	s_waitcnt lgkmcnt(0)
	v_mfma_f32_16x16x32_bf16 v[124:127], v[128:131], v[160:163], v[124:127]
	v_mfma_f32_16x16x32_bf16 v[120:123], v[136:139], v[160:163], v[120:123]
	v_mfma_f32_16x16x32_bf16 v[112:115], v[128:131], v[168:171], v[112:115]
	v_mfma_f32_16x16x32_bf16 v[104:107], v[136:139], v[168:171], v[104:107]
	v_mfma_f32_16x16x32_bf16 v[96:99], v[128:131], v[190:193], v[96:99]
	v_mfma_f32_16x16x32_bf16 v[88:91], v[136:139], v[190:193], v[88:91]
	v_mfma_f32_16x16x32_bf16 v[84:87], v[128:131], v[198:201], v[84:87]
	v_mfma_f32_16x16x32_bf16 v[76:79], v[136:139], v[198:201], v[76:79]
	v_mfma_f32_16x16x32_bf16 v[124:127], v[132:135], v[164:167], v[124:127]
	v_mfma_f32_16x16x32_bf16 v[120:123], v[140:143], v[164:167], v[120:123]
	v_mfma_f32_16x16x32_bf16 v[112:115], v[132:135], v[172:175], v[112:115]
	v_mfma_f32_16x16x32_bf16 v[104:107], v[140:143], v[172:175], v[104:107]
	v_mfma_f32_16x16x32_bf16 v[96:99], v[132:135], v[194:197], v[96:99]
	v_mfma_f32_16x16x32_bf16 v[88:91], v[140:143], v[194:197], v[88:91]
	v_mfma_f32_16x16x32_bf16 v[84:87], v[132:135], v[216:219], v[84:87]
	v_mfma_f32_16x16x32_bf16 v[76:79], v[140:143], v[216:219], v[76:79]
	s_setprio 0
	s_setprio 1
	v_mfma_f32_16x16x32_bf16 v[116:119], v[144:147], v[160:163], v[116:119]
	v_mfma_f32_16x16x32_bf16 v[108:111], v[152:155], v[160:163], v[108:111]
	v_mfma_f32_16x16x32_bf16 v[100:103], v[144:147], v[168:171], v[100:103]
	v_mfma_f32_16x16x32_bf16 v[92:95], v[152:155], v[168:171], v[92:95]
	v_mfma_f32_16x16x32_bf16 v[80:83], v[144:147], v[190:193], v[80:83]
	v_mfma_f32_16x16x32_bf16 v[72:75], v[152:155], v[190:193], v[72:75]
	v_mfma_f32_16x16x32_bf16 v[68:71], v[144:147], v[198:201], v[68:71]
	v_mfma_f32_16x16x32_bf16 v[64:67], v[152:155], v[198:201], v[64:67]
	v_mfma_f32_16x16x32_bf16 v[116:119], v[148:151], v[164:167], v[116:119]
	v_mfma_f32_16x16x32_bf16 v[108:111], v[156:159], v[164:167], v[108:111]
	v_mfma_f32_16x16x32_bf16 v[100:103], v[148:151], v[172:175], v[100:103]
	v_mfma_f32_16x16x32_bf16 v[92:95], v[156:159], v[172:175], v[92:95]
	v_mfma_f32_16x16x32_bf16 v[80:83], v[148:151], v[194:197], v[80:83]
	v_mfma_f32_16x16x32_bf16 v[72:75], v[156:159], v[194:197], v[72:75]
	v_mfma_f32_16x16x32_bf16 v[68:71], v[148:151], v[216:219], v[68:71]
	v_mfma_f32_16x16x32_bf16 v[64:67], v[156:159], v[216:219], v[64:67]
	s_setprio 0
	s_barrier
	s_add_i32 s24, s55, s27
	v_lshl_add_u64 v[202:203], v[202:203], 0, s[6:7]
	s_mov_b32 m0, s24
	ds_read_b128 v[160:163], v214 offset:49152
	ds_read_b128 v[164:167], v214 offset:50176
	ds_read_b128 v[168:171], v214 offset:51200
	ds_read_b128 v[172:175], v214 offset:52224
	ds_read_b128 v[190:193], v214 offset:53248
	ds_read_b128 v[194:197], v214 offset:54272
	ds_read_b128 v[198:201], v214 offset:55296
	ds_read_b128 v[216:219], v214 offset:56320
	global_load_lds_dwordx4 v[202:203], off
	s_add_i32 m0, s24, 0x2000
	s_add_u32 s22, s22, 0x40080
	v_lshl_add_u64 v[202:203], v[220:221], 0, s[6:7]
	s_addc_u32 s23, s23, 0
	s_add_i32 s24, s56, s27
	global_load_lds_dwordx4 v[202:203], off
	v_lshl_add_u64 v[202:203], s[22:23], 0, v[176:177]
	s_mov_b32 m0, s24
	s_nop 0
	global_load_lds_dwordx4 v176, s[22:23]
	v_lshl_add_u64 v[202:203], s[22:23], 0, v[178:179]
	s_add_i32 m0, s24, 0x2000
	s_nop 0
	global_load_lds_dwordx4 v178, s[22:23]
	v_lshl_add_u64 v[202:203], v[222:223], 0, s[6:7]
	s_mov_b32 m0, s40
	s_nop 0
	global_load_lds_dwordx4 v[202:203], off
	v_lshl_add_u64 v[202:203], v[224:225], 0, s[6:7]
	s_mov_b32 m0, s41
	s_nop 0
	global_load_lds_dwordx4 v[202:203], off
	s_waitcnt vmcnt(8)
	s_waitcnt lgkmcnt(0)
	s_barrier
	s_setprio 1
	s_waitcnt lgkmcnt(0)
	v_mfma_f32_16x16x32_bf16 v[60:63], v[128:131], v[160:163], v[60:63]
	v_mfma_f32_16x16x32_bf16 v[56:59], v[136:139], v[160:163], v[56:59]
	v_mfma_f32_16x16x32_bf16 v[48:51], v[128:131], v[168:171], v[48:51]
	v_mfma_f32_16x16x32_bf16 v[40:43], v[136:139], v[168:171], v[40:43]
	v_mfma_f32_16x16x32_bf16 v[32:35], v[128:131], v[190:193], v[32:35]
	v_mfma_f32_16x16x32_bf16 v[24:27], v[136:139], v[190:193], v[24:27]
	v_mfma_f32_16x16x32_bf16 v[20:23], v[128:131], v[198:201], v[20:23]
	v_mfma_f32_16x16x32_bf16 v[12:15], v[136:139], v[198:201], v[12:15]
	v_mfma_f32_16x16x32_bf16 v[60:63], v[132:135], v[164:167], v[60:63]
	v_mfma_f32_16x16x32_bf16 v[56:59], v[140:143], v[164:167], v[56:59]
	v_mfma_f32_16x16x32_bf16 v[48:51], v[132:135], v[172:175], v[48:51]
	v_mfma_f32_16x16x32_bf16 v[40:43], v[140:143], v[172:175], v[40:43]
	v_mfma_f32_16x16x32_bf16 v[32:35], v[132:135], v[194:197], v[32:35]
	v_mfma_f32_16x16x32_bf16 v[24:27], v[140:143], v[194:197], v[24:27]
	v_mfma_f32_16x16x32_bf16 v[20:23], v[132:135], v[216:219], v[20:23]
	v_mfma_f32_16x16x32_bf16 v[12:15], v[140:143], v[216:219], v[12:15]
	s_setprio 0
	s_setprio 1
	v_mfma_f32_16x16x32_bf16 v[52:55], v[144:147], v[160:163], v[52:55]
	v_mfma_f32_16x16x32_bf16 v[44:47], v[152:155], v[160:163], v[44:47]
	v_mfma_f32_16x16x32_bf16 v[36:39], v[144:147], v[168:171], v[36:39]
	v_mfma_f32_16x16x32_bf16 v[28:31], v[152:155], v[168:171], v[28:31]
	v_mfma_f32_16x16x32_bf16 v[16:19], v[144:147], v[190:193], v[16:19]
	v_mfma_f32_16x16x32_bf16 v[8:11], v[152:155], v[190:193], v[8:11]
	v_mfma_f32_16x16x32_bf16 v[4:7], v[144:147], v[198:201], v[4:7]
	v_mfma_f32_16x16x32_bf16 v[0:3], v[152:155], v[198:201], v[0:3]
	v_mfma_f32_16x16x32_bf16 v[52:55], v[148:151], v[164:167], v[52:55]
	v_mfma_f32_16x16x32_bf16 v[44:47], v[156:159], v[164:167], v[44:47]
	v_mfma_f32_16x16x32_bf16 v[36:39], v[148:151], v[172:175], v[36:39]
	v_mfma_f32_16x16x32_bf16 v[28:31], v[156:159], v[172:175], v[28:31]
	v_mfma_f32_16x16x32_bf16 v[16:19], v[148:151], v[194:197], v[16:19]
	v_mfma_f32_16x16x32_bf16 v[8:11], v[156:159], v[194:197], v[8:11]
	v_mfma_f32_16x16x32_bf16 v[4:7], v[148:151], v[216:219], v[4:7]
	v_mfma_f32_16x16x32_bf16 v[0:3], v[156:159], v[216:219], v[0:3]
	s_setprio 0
	s_barrier
	s_add_i32 s54, s54, 2
	s_add_u32 s20, s20, 0x100
	s_addc_u32 s21, s21, 0
	s_add_u32 s52, s52, 0x100
	s_addc_u32 s53, s53, 0
	s_cmp_gt_u32 s54, 13
	s_cbranch_scc0 .LBB0_1088
	s_and_b64 vcc, exec, s[8:9]
	s_cbranch_vccz .LBB0_1091
	s_barrier

.Llsb_skip_9:
.LBB0_1243:
	ds_read_b128 v[150:153], v147
	ds_read_b128 v[154:157], v147 offset:1024
	ds_read_b128 v[158:161], v147 offset:2048
	ds_read_b128 v[162:165], v147 offset:3072
	ds_read_b128 v[166:169], v148
	ds_read_b128 v[170:173], v148 offset:1024
	ds_read_b128 v[174:177], v148 offset:2048
	ds_read_b128 v[178:181], v148 offset:3072
	s_add_u32 s24, s22, 0xfffc0080
	s_addc_u32 s25, s23, -1
	s_cmp_eq_u32 s51, 12
	s_cselect_b32 s27, s15, s25
	s_cselect_b32 s26, s47, s24
	s_cselect_b32 s25, s13, s50
	s_cselect_b32 s24, s48, s49
	s_add_i32 m0, s21, 0xc000
	ds_read_b128 v[182:185], v149
	ds_read_b128 v[186:189], v149 offset:1024
	ds_read_b128 v[190:193], v149 offset:2048
	ds_read_b128 v[194:197], v149 offset:3072
	ds_read_b128 v[198:201], v149 offset:4096
	ds_read_b128 v[206:209], v149 offset:5120
	ds_read_b128 v[210:213], v149 offset:6144
	ds_read_b128 v[214:217], v149 offset:7168
	global_load_lds_dwordx4 v136, s[22:23]
	s_add_i32 m0, s21, 0xe000
	s_nop 0
	global_load_lds_dwordx4 v138, s[22:23]
	s_waitcnt vmcnt(8)
	s_waitcnt lgkmcnt(0)
	s_barrier
	s_setprio 1
	s_waitcnt lgkmcnt(0)
	v_mfma_f32_16x16x32_bf16 v[124:127], v[150:153], v[182:185], v[124:127]
	v_mfma_f32_16x16x32_bf16 v[120:123], v[158:161], v[182:185], v[120:123]
	v_mfma_f32_16x16x32_bf16 v[108:111], v[150:153], v[190:193], v[108:111]
	v_mfma_f32_16x16x32_bf16 v[104:107], v[158:161], v[190:193], v[104:107]
	v_mfma_f32_16x16x32_bf16 v[92:95], v[150:153], v[198:201], v[92:95]
	v_mfma_f32_16x16x32_bf16 v[88:91], v[158:161], v[198:201], v[88:91]
	v_mfma_f32_16x16x32_bf16 v[76:79], v[150:153], v[210:213], v[76:79]
	v_mfma_f32_16x16x32_bf16 v[72:75], v[158:161], v[210:213], v[72:75]
	v_mfma_f32_16x16x32_bf16 v[124:127], v[154:157], v[186:189], v[124:127]
	v_mfma_f32_16x16x32_bf16 v[120:123], v[162:165], v[186:189], v[120:123]
	v_mfma_f32_16x16x32_bf16 v[108:111], v[154:157], v[194:197], v[108:111]
	v_mfma_f32_16x16x32_bf16 v[104:107], v[162:165], v[194:197], v[104:107]
	v_mfma_f32_16x16x32_bf16 v[92:95], v[154:157], v[206:209], v[92:95]
	v_mfma_f32_16x16x32_bf16 v[88:91], v[162:165], v[206:209], v[88:91]
	v_mfma_f32_16x16x32_bf16 v[76:79], v[154:157], v[214:217], v[76:79]
	v_mfma_f32_16x16x32_bf16 v[72:75], v[162:165], v[214:217], v[72:75]
	s_setprio 0
	s_setprio 1
	v_mfma_f32_16x16x32_bf16 v[116:119], v[166:169], v[182:185], v[116:119]
	v_mfma_f32_16x16x32_bf16 v[112:115], v[174:177], v[182:185], v[112:115]
	v_mfma_f32_16x16x32_bf16 v[100:103], v[166:169], v[190:193], v[100:103]
	v_mfma_f32_16x16x32_bf16 v[96:99], v[174:177], v[190:193], v[96:99]
	v_mfma_f32_16x16x32_bf16 v[84:87], v[166:169], v[198:201], v[84:87]
	v_mfma_f32_16x16x32_bf16 v[80:83], v[174:177], v[198:201], v[80:83]
	v_mfma_f32_16x16x32_bf16 v[68:71], v[166:169], v[210:213], v[68:71]
	v_mfma_f32_16x16x32_bf16 v[64:67], v[174:177], v[210:213], v[64:67]
	v_mfma_f32_16x16x32_bf16 v[116:119], v[170:173], v[186:189], v[116:119]
	v_mfma_f32_16x16x32_bf16 v[112:115], v[178:181], v[186:189], v[112:115]
	v_mfma_f32_16x16x32_bf16 v[100:103], v[170:173], v[194:197], v[100:103]
	v_mfma_f32_16x16x32_bf16 v[96:99], v[178:181], v[194:197], v[96:99]
	v_mfma_f32_16x16x32_bf16 v[84:87], v[170:173], v[206:209], v[84:87]
	v_mfma_f32_16x16x32_bf16 v[80:83], v[178:181], v[206:209], v[80:83]
	v_mfma_f32_16x16x32_bf16 v[68:71], v[170:173], v[214:217], v[68:71]
	v_mfma_f32_16x16x32_bf16 v[64:67], v[178:181], v[214:217], v[64:67]
	s_setprio 0
	s_barrier
	s_add_i32 s52, s43, s34
	v_lshl_add_u64 v[202:203], s[24:25], 0, v[130:131]
	s_mov_b32 m0, s52
	ds_read_b128 v[182:185], v149 offset:16384
	ds_read_b128 v[186:189], v149 offset:17408
	ds_read_b128 v[190:193], v149 offset:18432
	ds_read_b128 v[194:197], v149 offset:19456
	ds_read_b128 v[198:201], v149 offset:20480
	ds_read_b128 v[206:209], v149 offset:21504
	ds_read_b128 v[210:213], v149 offset:22528
	ds_read_b128 v[214:217], v149 offset:23552
	global_load_lds_dwordx4 v130, s[24:25]
	s_add_i32 m0, s52, 0x2000
	s_add_u32 s52, s24, 0x40000
	v_lshl_add_u64 v[218:219], s[24:25], 0, v[134:135]
	s_addc_u32 s53, s25, 0
	s_add_i32 s54, s44, s34
	global_load_lds_dwordx4 v134, s[24:25]
	s_mov_b32 m0, s54
	v_lshl_add_u64 v[222:223], s[26:27], 0, v[132:133]
	global_load_lds_dwordx4 v130, s[52:53]
	s_add_i32 m0, s54, 0x2000
	s_nop 0
	global_load_lds_dwordx4 v134, s[52:53]
	v_lshl_add_u64 v[220:221], s[26:27], 0, v[128:129]
	s_mov_b32 m0, s21
	s_nop 0
	global_load_lds_dwordx4 v128, s[26:27]
	s_mov_b32 m0, s35
	s_nop 0
	global_load_lds_dwordx4 v132, s[26:27]
	s_waitcnt vmcnt(8)
	s_waitcnt lgkmcnt(0)
	s_barrier
	s_setprio 1
	s_waitcnt lgkmcnt(0)
	v_mfma_f32_16x16x32_bf16 v[60:63], v[150:153], v[182:185], v[60:63]
	v_mfma_f32_16x16x32_bf16 v[56:59], v[158:161], v[182:185], v[56:59]
	v_mfma_f32_16x16x32_bf16 v[44:47], v[150:153], v[190:193], v[44:47]
	v_mfma_f32_16x16x32_bf16 v[40:43], v[158:161], v[190:193], v[40:43]
	v_mfma_f32_16x16x32_bf16 v[28:31], v[150:153], v[198:201], v[28:31]
	v_mfma_f32_16x16x32_bf16 v[24:27], v[158:161], v[198:201], v[24:27]
	v_mfma_f32_16x16x32_bf16 v[12:15], v[150:153], v[210:213], v[12:15]
	v_mfma_f32_16x16x32_bf16 v[8:11], v[158:161], v[210:213], v[8:11]
	v_mfma_f32_16x16x32_bf16 v[60:63], v[154:157], v[186:189], v[60:63]
	v_mfma_f32_16x16x32_bf16 v[56:59], v[162:165], v[186:189], v[56:59]
	v_mfma_f32_16x16x32_bf16 v[44:47], v[154:157], v[194:197], v[44:47]
	v_mfma_f32_16x16x32_bf16 v[40:43], v[162:165], v[194:197], v[40:43]
	v_mfma_f32_16x16x32_bf16 v[28:31], v[154:157], v[206:209], v[28:31]
	v_mfma_f32_16x16x32_bf16 v[24:27], v[162:165], v[206:209], v[24:27]
	v_mfma_f32_16x16x32_bf16 v[12:15], v[154:157], v[214:217], v[12:15]
	v_mfma_f32_16x16x32_bf16 v[8:11], v[162:165], v[214:217], v[8:11]
	s_setprio 0
	s_setprio 1
	v_mfma_f32_16x16x32_bf16 v[52:55], v[166:169], v[182:185], v[52:55]
	v_mfma_f32_16x16x32_bf16 v[48:51], v[174:177], v[182:185], v[48:51]
	v_mfma_f32_16x16x32_bf16 v[36:39], v[166:169], v[190:193], v[36:39]
	v_mfma_f32_16x16x32_bf16 v[32:35], v[174:177], v[190:193], v[32:35]
	v_mfma_f32_16x16x32_bf16 v[20:23], v[166:169], v[198:201], v[20:23]
	v_mfma_f32_16x16x32_bf16 v[16:19], v[174:177], v[198:201], v[16:19]
	v_mfma_f32_16x16x32_bf16 v[4:7], v[166:169], v[210:213], v[4:7]
	v_mfma_f32_16x16x32_bf16 v[0:3], v[174:177], v[210:213], v[0:3]
	v_mfma_f32_16x16x32_bf16 v[52:55], v[170:173], v[186:189], v[52:55]
	v_mfma_f32_16x16x32_bf16 v[48:51], v[178:181], v[186:189], v[48:51]
	v_mfma_f32_16x16x32_bf16 v[36:39], v[170:173], v[194:197], v[36:39]
	v_mfma_f32_16x16x32_bf16 v[32:35], v[178:181], v[194:197], v[32:35]
	v_mfma_f32_16x16x32_bf16 v[20:23], v[170:173], v[206:209], v[20:23]
	v_mfma_f32_16x16x32_bf16 v[16:19], v[178:181], v[206:209], v[16:19]
	v_mfma_f32_16x16x32_bf16 v[4:7], v[170:173], v[214:217], v[4:7]
	v_mfma_f32_16x16x32_bf16 v[0:3], v[178:181], v[214:217], v[0:3]
	s_setprio 0
	s_barrier
	s_add_i32 s52, 0, 0x18000
	s_add_i32 s53, 0, 0x1c000
	v_add_u32_e32 v162, s52, v145
	v_add_u32_e32 v178, s53, v145
	ds_read_b128 v[150:153], v162
	ds_read_b128 v[154:157], v162 offset:1024
	ds_read_b128 v[158:161], v162 offset:2048
	ds_read_b128 v[162:165], v162 offset:3072
	ds_read_b128 v[166:169], v178
	ds_read_b128 v[170:173], v178 offset:1024
	ds_read_b128 v[174:177], v178 offset:2048
	ds_read_b128 v[178:181], v178 offset:3072
	s_add_u32 s26, s26, 0x40000
	s_addc_u32 s27, s27, 0
	s_mov_b32 m0, s36
	ds_read_b128 v[182:185], v149 offset:32768
	ds_read_b128 v[186:189], v149 offset:33792
	ds_read_b128 v[190:193], v149 offset:34816
	ds_read_b128 v[194:197], v149 offset:35840
	ds_read_b128 v[198:201], v149 offset:36864
	ds_read_b128 v[206:209], v149 offset:37888
	ds_read_b128 v[210:213], v149 offset:38912
	ds_read_b128 v[214:217], v149 offset:39936
	global_load_lds_dwordx4 v128, s[26:27]
	s_mov_b32 m0, s37
	s_nop 0
	global_load_lds_dwordx4 v132, s[26:27]
	s_waitcnt vmcnt(8)
	s_waitcnt lgkmcnt(0)
	s_barrier
	s_setprio 1
	s_waitcnt lgkmcnt(0)
	v_mfma_f32_16x16x32_bf16 v[124:127], v[150:153], v[182:185], v[124:127]
	v_mfma_f32_16x16x32_bf16 v[120:123], v[158:161], v[182:185], v[120:123]
	v_mfma_f32_16x16x32_bf16 v[108:111], v[150:153], v[190:193], v[108:111]
	v_mfma_f32_16x16x32_bf16 v[104:107], v[158:161], v[190:193], v[104:107]
	v_mfma_f32_16x16x32_bf16 v[92:95], v[150:153], v[198:201], v[92:95]
	v_mfma_f32_16x16x32_bf16 v[88:91], v[158:161], v[198:201], v[88:91]
	v_mfma_f32_16x16x32_bf16 v[76:79], v[150:153], v[210:213], v[76:79]
	v_mfma_f32_16x16x32_bf16 v[72:75], v[158:161], v[210:213], v[72:75]
	v_mfma_f32_16x16x32_bf16 v[124:127], v[154:157], v[186:189], v[124:127]
	v_mfma_f32_16x16x32_bf16 v[120:123], v[162:165], v[186:189], v[120:123]
	v_mfma_f32_16x16x32_bf16 v[108:111], v[154:157], v[194:197], v[108:111]
	v_mfma_f32_16x16x32_bf16 v[104:107], v[162:165], v[194:197], v[104:107]
	v_mfma_f32_16x16x32_bf16 v[92:95], v[154:157], v[206:209], v[92:95]
	v_mfma_f32_16x16x32_bf16 v[88:91], v[162:165], v[206:209], v[88:91]
	v_mfma_f32_16x16x32_bf16 v[76:79], v[154:157], v[214:217], v[76:79]
	v_mfma_f32_16x16x32_bf16 v[72:75], v[162:165], v[214:217], v[72:75]
	s_setprio 0
	s_setprio 1
	v_mfma_f32_16x16x32_bf16 v[116:119], v[166:169], v[182:185], v[116:119]
	v_mfma_f32_16x16x32_bf16 v[112:115], v[174:177], v[182:185], v[112:115]
	v_mfma_f32_16x16x32_bf16 v[100:103], v[166:169], v[190:193], v[100:103]
	v_mfma_f32_16x16x32_bf16 v[96:99], v[174:177], v[190:193], v[96:99]
	v_mfma_f32_16x16x32_bf16 v[84:87], v[166:169], v[198:201], v[84:87]
	v_mfma_f32_16x16x32_bf16 v[80:83], v[174:177], v[198:201], v[80:83]
	v_mfma_f32_16x16x32_bf16 v[68:71], v[166:169], v[210:213], v[68:71]
	v_mfma_f32_16x16x32_bf16 v[64:67], v[174:177], v[210:213], v[64:67]
	v_mfma_f32_16x16x32_bf16 v[116:119], v[170:173], v[186:189], v[116:119]
	v_mfma_f32_16x16x32_bf16 v[112:115], v[178:181], v[186:189], v[112:115]
	v_mfma_f32_16x16x32_bf16 v[100:103], v[170:173], v[194:197], v[100:103]
	v_mfma_f32_16x16x32_bf16 v[96:99], v[178:181], v[194:197], v[96:99]
	v_mfma_f32_16x16x32_bf16 v[84:87], v[170:173], v[206:209], v[84:87]
	v_mfma_f32_16x16x32_bf16 v[80:83], v[178:181], v[206:209], v[80:83]
	v_mfma_f32_16x16x32_bf16 v[68:71], v[170:173], v[214:217], v[68:71]
	v_mfma_f32_16x16x32_bf16 v[64:67], v[178:181], v[214:217], v[64:67]
	s_setprio 0
	s_barrier
	s_add_i32 s26, s52, s34
	v_lshl_add_u64 v[202:203], v[202:203], 0, s[8:9]
	s_mov_b32 m0, s26
	ds_read_b128 v[182:185], v149 offset:49152
	ds_read_b128 v[186:189], v149 offset:50176
	ds_read_b128 v[190:193], v149 offset:51200
	ds_read_b128 v[194:197], v149 offset:52224
	ds_read_b128 v[198:201], v149 offset:53248
	ds_read_b128 v[206:209], v149 offset:54272
	ds_read_b128 v[210:213], v149 offset:55296
	ds_read_b128 v[214:217], v149 offset:56320
	global_load_lds_dwordx4 v[202:203], off
	s_add_i32 m0, s26, 0x2000
	s_add_u32 s24, s24, 0x40080
	v_lshl_add_u64 v[202:203], v[218:219], 0, s[8:9]
	s_addc_u32 s25, s25, 0
	s_add_i32 s26, s53, s34
	global_load_lds_dwordx4 v[202:203], off
	s_mov_b32 m0, s26
	s_nop 0
	global_load_lds_dwordx4 v130, s[24:25]
	s_add_i32 m0, s26, 0x2000
	s_nop 0
	global_load_lds_dwordx4 v134, s[24:25]
	v_lshl_add_u64 v[202:203], v[220:221], 0, s[8:9]
	s_mov_b32 m0, s40
	s_nop 0
	global_load_lds_dwordx4 v[202:203], off
	v_lshl_add_u64 v[202:203], v[222:223], 0, s[8:9]
	s_mov_b32 m0, s41
	s_nop 0
	global_load_lds_dwordx4 v[202:203], off
	s_waitcnt vmcnt(8)
	s_waitcnt lgkmcnt(0)
	s_barrier
	s_setprio 1
	s_waitcnt lgkmcnt(0)
	v_mfma_f32_16x16x32_bf16 v[60:63], v[150:153], v[182:185], v[60:63]
	v_mfma_f32_16x16x32_bf16 v[56:59], v[158:161], v[182:185], v[56:59]
	v_mfma_f32_16x16x32_bf16 v[44:47], v[150:153], v[190:193], v[44:47]
	v_mfma_f32_16x16x32_bf16 v[40:43], v[158:161], v[190:193], v[40:43]
	v_mfma_f32_16x16x32_bf16 v[28:31], v[150:153], v[198:201], v[28:31]
	v_mfma_f32_16x16x32_bf16 v[24:27], v[158:161], v[198:201], v[24:27]
	v_mfma_f32_16x16x32_bf16 v[12:15], v[150:153], v[210:213], v[12:15]
	v_mfma_f32_16x16x32_bf16 v[8:11], v[158:161], v[210:213], v[8:11]
	v_mfma_f32_16x16x32_bf16 v[60:63], v[154:157], v[186:189], v[60:63]
	v_mfma_f32_16x16x32_bf16 v[56:59], v[162:165], v[186:189], v[56:59]
	v_mfma_f32_16x16x32_bf16 v[44:47], v[154:157], v[194:197], v[44:47]
	v_mfma_f32_16x16x32_bf16 v[40:43], v[162:165], v[194:197], v[40:43]
	v_mfma_f32_16x16x32_bf16 v[28:31], v[154:157], v[206:209], v[28:31]
	v_mfma_f32_16x16x32_bf16 v[24:27], v[162:165], v[206:209], v[24:27]
	v_mfma_f32_16x16x32_bf16 v[12:15], v[154:157], v[214:217], v[12:15]
	v_mfma_f32_16x16x32_bf16 v[8:11], v[162:165], v[214:217], v[8:11]
	s_setprio 0
	s_setprio 1
	v_mfma_f32_16x16x32_bf16 v[52:55], v[166:169], v[182:185], v[52:55]
	v_mfma_f32_16x16x32_bf16 v[48:51], v[174:177], v[182:185], v[48:51]
	v_mfma_f32_16x16x32_bf16 v[36:39], v[166:169], v[190:193], v[36:39]
	v_mfma_f32_16x16x32_bf16 v[32:35], v[174:177], v[190:193], v[32:35]
	v_mfma_f32_16x16x32_bf16 v[20:23], v[166:169], v[198:201], v[20:23]
	v_mfma_f32_16x16x32_bf16 v[16:19], v[174:177], v[198:201], v[16:19]
	v_mfma_f32_16x16x32_bf16 v[4:7], v[166:169], v[210:213], v[4:7]
	v_mfma_f32_16x16x32_bf16 v[0:3], v[174:177], v[210:213], v[0:3]
	v_mfma_f32_16x16x32_bf16 v[52:55], v[170:173], v[186:189], v[52:55]
	v_mfma_f32_16x16x32_bf16 v[48:51], v[178:181], v[186:189], v[48:51]
	v_mfma_f32_16x16x32_bf16 v[36:39], v[170:173], v[194:197], v[36:39]
	v_mfma_f32_16x16x32_bf16 v[32:35], v[178:181], v[194:197], v[32:35]
	v_mfma_f32_16x16x32_bf16 v[20:23], v[170:173], v[206:209], v[20:23]
	v_mfma_f32_16x16x32_bf16 v[16:19], v[178:181], v[206:209], v[16:19]
	v_mfma_f32_16x16x32_bf16 v[4:7], v[170:173], v[214:217], v[4:7]
	v_mfma_f32_16x16x32_bf16 v[0:3], v[178:181], v[214:217], v[0:3]
	s_setprio 0
	s_barrier
	s_add_i32 s51, s51, 2
	s_add_u32 s22, s22, 0x100
	s_addc_u32 s23, s23, 0
	s_add_u32 s49, s49, 0x100
	s_addc_u32 s50, s50, 0
	s_cmp_gt_u32 s51, 13
	s_cbranch_scc0 .LBB0_1243
	s_and_b64 vcc, exec, s[10:11]
	s_cbranch_vccz .LBB0_1246
	s_barrier

.Llsb_skip_10:
.LBB0_1324:
	ds_read_b128 v[128:131], v212
	ds_read_b128 v[132:135], v212 offset:1024
	ds_read_b128 v[136:139], v212 offset:2048
	ds_read_b128 v[140:143], v212 offset:3072
	ds_read_b128 v[144:147], v213
	ds_read_b128 v[148:151], v213 offset:1024
	ds_read_b128 v[152:155], v213 offset:2048
	ds_read_b128 v[156:159], v213 offset:3072
	s_add_u32 s18, s16, 0xfff50080
	s_addc_u32 s19, s17, -1
	s_cmp_eq_u32 s52, 40
	s_cselect_b32 s21, s5, s19
	s_cselect_b32 s20, s4, s18
	s_cselect_b32 s19, s15, s51
	s_cselect_b32 s18, s14, s50
	s_add_i32 m0, s23, 0xc000
	ds_read_b128 v[160:163], v214
	ds_read_b128 v[164:167], v214 offset:1024
	ds_read_b128 v[168:171], v214 offset:2048
	ds_read_b128 v[172:175], v214 offset:3072
	ds_read_b128 v[190:193], v214 offset:4096
	ds_read_b128 v[194:197], v214 offset:5120
	ds_read_b128 v[198:201], v214 offset:6144
	ds_read_b128 v[216:219], v214 offset:7168
	global_load_lds_dwordx4 v182, s[16:17]
	s_add_i32 m0, s23, 0xe000
	s_nop 0
	global_load_lds_dwordx4 v184, s[16:17]
	s_waitcnt vmcnt(8)
	s_waitcnt lgkmcnt(0)
	s_barrier
	s_setprio 1
	s_waitcnt lgkmcnt(0)
	v_mfma_f32_16x16x32_bf16 v[124:127], v[128:131], v[160:163], v[124:127]
	v_mfma_f32_16x16x32_bf16 v[120:123], v[136:139], v[160:163], v[120:123]
	v_mfma_f32_16x16x32_bf16 v[112:115], v[128:131], v[168:171], v[112:115]
	v_mfma_f32_16x16x32_bf16 v[104:107], v[136:139], v[168:171], v[104:107]
	v_mfma_f32_16x16x32_bf16 v[96:99], v[128:131], v[190:193], v[96:99]
	v_mfma_f32_16x16x32_bf16 v[88:91], v[136:139], v[190:193], v[88:91]
	v_mfma_f32_16x16x32_bf16 v[84:87], v[128:131], v[198:201], v[84:87]
	v_mfma_f32_16x16x32_bf16 v[76:79], v[136:139], v[198:201], v[76:79]
	v_mfma_f32_16x16x32_bf16 v[124:127], v[132:135], v[164:167], v[124:127]
	v_mfma_f32_16x16x32_bf16 v[120:123], v[140:143], v[164:167], v[120:123]
	v_mfma_f32_16x16x32_bf16 v[112:115], v[132:135], v[172:175], v[112:115]
	v_mfma_f32_16x16x32_bf16 v[104:107], v[140:143], v[172:175], v[104:107]
	v_mfma_f32_16x16x32_bf16 v[96:99], v[132:135], v[194:197], v[96:99]
	v_mfma_f32_16x16x32_bf16 v[88:91], v[140:143], v[194:197], v[88:91]
	v_mfma_f32_16x16x32_bf16 v[84:87], v[132:135], v[216:219], v[84:87]
	v_mfma_f32_16x16x32_bf16 v[76:79], v[140:143], v[216:219], v[76:79]
	s_setprio 0
	s_setprio 1
	v_mfma_f32_16x16x32_bf16 v[116:119], v[144:147], v[160:163], v[116:119]
	v_mfma_f32_16x16x32_bf16 v[108:111], v[152:155], v[160:163], v[108:111]
	v_mfma_f32_16x16x32_bf16 v[100:103], v[144:147], v[168:171], v[100:103]
	v_mfma_f32_16x16x32_bf16 v[92:95], v[152:155], v[168:171], v[92:95]
	v_mfma_f32_16x16x32_bf16 v[80:83], v[144:147], v[190:193], v[80:83]
	v_mfma_f32_16x16x32_bf16 v[72:75], v[152:155], v[190:193], v[72:75]
	v_mfma_f32_16x16x32_bf16 v[68:71], v[144:147], v[198:201], v[68:71]
	v_mfma_f32_16x16x32_bf16 v[64:67], v[152:155], v[198:201], v[64:67]
	v_mfma_f32_16x16x32_bf16 v[116:119], v[148:151], v[164:167], v[116:119]
	v_mfma_f32_16x16x32_bf16 v[108:111], v[156:159], v[164:167], v[108:111]
	v_mfma_f32_16x16x32_bf16 v[100:103], v[148:151], v[172:175], v[100:103]
	v_mfma_f32_16x16x32_bf16 v[92:95], v[156:159], v[172:175], v[92:95]
	v_mfma_f32_16x16x32_bf16 v[80:83], v[148:151], v[194:197], v[80:83]
	v_mfma_f32_16x16x32_bf16 v[72:75], v[156:159], v[194:197], v[72:75]
	v_mfma_f32_16x16x32_bf16 v[68:71], v[148:151], v[216:219], v[68:71]
	v_mfma_f32_16x16x32_bf16 v[64:67], v[156:159], v[216:219], v[64:67]
	s_setprio 0
	s_barrier
	s_add_i32 s53, s35, s22
	v_lshl_add_u64 v[202:203], s[18:19], 0, v[176:177]
	s_mov_b32 m0, s53
	ds_read_b128 v[160:163], v214 offset:16384
	ds_read_b128 v[164:167], v214 offset:17408
	ds_read_b128 v[168:171], v214 offset:18432
	ds_read_b128 v[172:175], v214 offset:19456
	ds_read_b128 v[190:193], v214 offset:20480
	ds_read_b128 v[194:197], v214 offset:21504
	ds_read_b128 v[198:201], v214 offset:22528
	ds_read_b128 v[216:219], v214 offset:23552
	global_load_lds_dwordx4 v176, s[18:19]
	s_add_i32 m0, s53, 0x2000
	s_add_u32 s54, s18, 0xb0000
	v_lshl_add_u64 v[220:221], s[18:19], 0, v[178:179]
	s_addc_u32 s55, s19, 0
	s_add_i32 s53, s40, s22
	global_load_lds_dwordx4 v178, s[18:19]
	s_mov_b32 m0, s53
	v_lshl_add_u64 v[224:225], s[20:21], 0, v[178:179]
	global_load_lds_dwordx4 v176, s[54:55]
	s_add_i32 m0, s53, 0x2000
	s_nop 0
	global_load_lds_dwordx4 v178, s[54:55]
	v_lshl_add_u64 v[222:223], s[20:21], 0, v[176:177]
	s_mov_b32 m0, s23
	s_nop 0
	global_load_lds_dwordx4 v176, s[20:21]
	s_mov_b32 m0, s24
	s_nop 0
	global_load_lds_dwordx4 v178, s[20:21]
	s_waitcnt vmcnt(8)
	s_waitcnt lgkmcnt(0)
	s_barrier
	s_setprio 1
	s_waitcnt lgkmcnt(0)
	v_mfma_f32_16x16x32_bf16 v[60:63], v[128:131], v[160:163], v[60:63]
	v_mfma_f32_16x16x32_bf16 v[56:59], v[136:139], v[160:163], v[56:59]
	v_mfma_f32_16x16x32_bf16 v[48:51], v[128:131], v[168:171], v[48:51]
	v_mfma_f32_16x16x32_bf16 v[40:43], v[136:139], v[168:171], v[40:43]
	v_mfma_f32_16x16x32_bf16 v[32:35], v[128:131], v[190:193], v[32:35]
	v_mfma_f32_16x16x32_bf16 v[24:27], v[136:139], v[190:193], v[24:27]
	v_mfma_f32_16x16x32_bf16 v[20:23], v[128:131], v[198:201], v[20:23]
	v_mfma_f32_16x16x32_bf16 v[12:15], v[136:139], v[198:201], v[12:15]
	v_mfma_f32_16x16x32_bf16 v[60:63], v[132:135], v[164:167], v[60:63]
	v_mfma_f32_16x16x32_bf16 v[56:59], v[140:143], v[164:167], v[56:59]
	v_mfma_f32_16x16x32_bf16 v[48:51], v[132:135], v[172:175], v[48:51]
	v_mfma_f32_16x16x32_bf16 v[40:43], v[140:143], v[172:175], v[40:43]
	v_mfma_f32_16x16x32_bf16 v[32:35], v[132:135], v[194:197], v[32:35]
	v_mfma_f32_16x16x32_bf16 v[24:27], v[140:143], v[194:197], v[24:27]
	v_mfma_f32_16x16x32_bf16 v[20:23], v[132:135], v[216:219], v[20:23]
	v_mfma_f32_16x16x32_bf16 v[12:15], v[140:143], v[216:219], v[12:15]
	s_setprio 0
	s_setprio 1
	v_mfma_f32_16x16x32_bf16 v[52:55], v[144:147], v[160:163], v[52:55]
	v_mfma_f32_16x16x32_bf16 v[44:47], v[152:155], v[160:163], v[44:47]
	v_mfma_f32_16x16x32_bf16 v[36:39], v[144:147], v[168:171], v[36:39]
	v_mfma_f32_16x16x32_bf16 v[28:31], v[152:155], v[168:171], v[28:31]
	v_mfma_f32_16x16x32_bf16 v[16:19], v[144:147], v[190:193], v[16:19]
	v_mfma_f32_16x16x32_bf16 v[8:11], v[152:155], v[190:193], v[8:11]
	v_mfma_f32_16x16x32_bf16 v[4:7], v[144:147], v[198:201], v[4:7]
	v_mfma_f32_16x16x32_bf16 v[0:3], v[152:155], v[198:201], v[0:3]
	v_mfma_f32_16x16x32_bf16 v[52:55], v[148:151], v[164:167], v[52:55]
	v_mfma_f32_16x16x32_bf16 v[44:47], v[156:159], v[164:167], v[44:47]
	v_mfma_f32_16x16x32_bf16 v[36:39], v[148:151], v[172:175], v[36:39]
	v_mfma_f32_16x16x32_bf16 v[28:31], v[156:159], v[172:175], v[28:31]
	v_mfma_f32_16x16x32_bf16 v[16:19], v[148:151], v[194:197], v[16:19]
	v_mfma_f32_16x16x32_bf16 v[8:11], v[156:159], v[194:197], v[8:11]
	v_mfma_f32_16x16x32_bf16 v[4:7], v[148:151], v[216:219], v[4:7]
	v_mfma_f32_16x16x32_bf16 v[0:3], v[156:159], v[216:219], v[0:3]
	s_setprio 0
	s_barrier
	s_add_i32 s53, 0, 0x18000
	s_add_i32 s54, 0, 0x1c000
	v_add_u32_e32 v140, s53, v210
	v_add_u32_e32 v156, s54, v210
	ds_read_b128 v[128:131], v140
	ds_read_b128 v[132:135], v140 offset:1024
	ds_read_b128 v[136:139], v140 offset:2048
	ds_read_b128 v[140:143], v140 offset:3072
	ds_read_b128 v[144:147], v156
	ds_read_b128 v[148:151], v156 offset:1024
	ds_read_b128 v[152:155], v156 offset:2048
	ds_read_b128 v[156:159], v156 offset:3072
	s_add_u32 s20, s20, 0xb0000
	s_addc_u32 s21, s21, 0
	s_mov_b32 m0, s25
	ds_read_b128 v[160:163], v214 offset:32768
	ds_read_b128 v[164:167], v214 offset:33792
	ds_read_b128 v[168:171], v214 offset:34816
	ds_read_b128 v[172:175], v214 offset:35840
	ds_read_b128 v[190:193], v214 offset:36864
	ds_read_b128 v[194:197], v214 offset:37888
	ds_read_b128 v[198:201], v214 offset:38912
	ds_read_b128 v[216:219], v214 offset:39936
	global_load_lds_dwordx4 v176, s[20:21]
	s_mov_b32 m0, s26
	s_nop 0
	global_load_lds_dwordx4 v178, s[20:21]
	s_waitcnt vmcnt(8)
	s_waitcnt lgkmcnt(0)
	s_barrier
	s_setprio 1
	s_waitcnt lgkmcnt(0)
	v_mfma_f32_16x16x32_bf16 v[124:127], v[128:131], v[160:163], v[124:127]
	v_mfma_f32_16x16x32_bf16 v[120:123], v[136:139], v[160:163], v[120:123]
	v_mfma_f32_16x16x32_bf16 v[112:115], v[128:131], v[168:171], v[112:115]
	v_mfma_f32_16x16x32_bf16 v[104:107], v[136:139], v[168:171], v[104:107]
	v_mfma_f32_16x16x32_bf16 v[96:99], v[128:131], v[190:193], v[96:99]
	v_mfma_f32_16x16x32_bf16 v[88:91], v[136:139], v[190:193], v[88:91]
	v_mfma_f32_16x16x32_bf16 v[84:87], v[128:131], v[198:201], v[84:87]
	v_mfma_f32_16x16x32_bf16 v[76:79], v[136:139], v[198:201], v[76:79]
	v_mfma_f32_16x16x32_bf16 v[124:127], v[132:135], v[164:167], v[124:127]
	v_mfma_f32_16x16x32_bf16 v[120:123], v[140:143], v[164:167], v[120:123]
	v_mfma_f32_16x16x32_bf16 v[112:115], v[132:135], v[172:175], v[112:115]
	v_mfma_f32_16x16x32_bf16 v[104:107], v[140:143], v[172:175], v[104:107]
	v_mfma_f32_16x16x32_bf16 v[96:99], v[132:135], v[194:197], v[96:99]
	v_mfma_f32_16x16x32_bf16 v[88:91], v[140:143], v[194:197], v[88:91]
	v_mfma_f32_16x16x32_bf16 v[84:87], v[132:135], v[216:219], v[84:87]
	v_mfma_f32_16x16x32_bf16 v[76:79], v[140:143], v[216:219], v[76:79]
	s_setprio 0
	s_setprio 1
	v_mfma_f32_16x16x32_bf16 v[116:119], v[144:147], v[160:163], v[116:119]
	v_mfma_f32_16x16x32_bf16 v[108:111], v[152:155], v[160:163], v[108:111]
	v_mfma_f32_16x16x32_bf16 v[100:103], v[144:147], v[168:171], v[100:103]
	v_mfma_f32_16x16x32_bf16 v[92:95], v[152:155], v[168:171], v[92:95]
	v_mfma_f32_16x16x32_bf16 v[80:83], v[144:147], v[190:193], v[80:83]
	v_mfma_f32_16x16x32_bf16 v[72:75], v[152:155], v[190:193], v[72:75]
	v_mfma_f32_16x16x32_bf16 v[68:71], v[144:147], v[198:201], v[68:71]
	v_mfma_f32_16x16x32_bf16 v[64:67], v[152:155], v[198:201], v[64:67]
	v_mfma_f32_16x16x32_bf16 v[116:119], v[148:151], v[164:167], v[116:119]
	v_mfma_f32_16x16x32_bf16 v[108:111], v[156:159], v[164:167], v[108:111]
	v_mfma_f32_16x16x32_bf16 v[100:103], v[148:151], v[172:175], v[100:103]
	v_mfma_f32_16x16x32_bf16 v[92:95], v[156:159], v[172:175], v[92:95]
	v_mfma_f32_16x16x32_bf16 v[80:83], v[148:151], v[194:197], v[80:83]
	v_mfma_f32_16x16x32_bf16 v[72:75], v[156:159], v[194:197], v[72:75]
	v_mfma_f32_16x16x32_bf16 v[68:71], v[148:151], v[216:219], v[68:71]
	v_mfma_f32_16x16x32_bf16 v[64:67], v[156:159], v[216:219], v[64:67]
	s_setprio 0
	s_barrier
	s_add_i32 s20, s53, s22
	v_lshl_add_u64 v[202:203], v[202:203], 0, s[10:11]
	s_mov_b32 m0, s20
	ds_read_b128 v[160:163], v214 offset:49152
	ds_read_b128 v[164:167], v214 offset:50176
	ds_read_b128 v[168:171], v214 offset:51200
	ds_read_b128 v[172:175], v214 offset:52224
	ds_read_b128 v[190:193], v214 offset:53248
	ds_read_b128 v[194:197], v214 offset:54272
	ds_read_b128 v[198:201], v214 offset:55296
	ds_read_b128 v[216:219], v214 offset:56320
	global_load_lds_dwordx4 v[202:203], off
	s_add_i32 m0, s20, 0x2000
	s_add_u32 s18, s18, 0xb0080
	v_lshl_add_u64 v[202:203], v[220:221], 0, s[10:11]
	s_addc_u32 s19, s19, 0
	s_add_i32 s20, s54, s22
	global_load_lds_dwordx4 v[202:203], off
	s_mov_b32 m0, s20
	s_nop 0
	global_load_lds_dwordx4 v176, s[18:19]
	s_add_i32 m0, s20, 0x2000
	s_nop 0
	global_load_lds_dwordx4 v178, s[18:19]
	v_lshl_add_u64 v[202:203], v[222:223], 0, s[10:11]
	s_mov_b32 m0, s29
	s_nop 0
	global_load_lds_dwordx4 v[202:203], off
	v_lshl_add_u64 v[202:203], v[224:225], 0, s[10:11]
	s_mov_b32 m0, s30
	s_nop 0
	global_load_lds_dwordx4 v[202:203], off
	s_waitcnt vmcnt(8)
	s_waitcnt lgkmcnt(0)
	s_barrier
	s_setprio 1
	s_waitcnt lgkmcnt(0)
	v_mfma_f32_16x16x32_bf16 v[60:63], v[128:131], v[160:163], v[60:63]
	v_mfma_f32_16x16x32_bf16 v[56:59], v[136:139], v[160:163], v[56:59]
	v_mfma_f32_16x16x32_bf16 v[48:51], v[128:131], v[168:171], v[48:51]
	v_mfma_f32_16x16x32_bf16 v[40:43], v[136:139], v[168:171], v[40:43]
	v_mfma_f32_16x16x32_bf16 v[32:35], v[128:131], v[190:193], v[32:35]
	v_mfma_f32_16x16x32_bf16 v[24:27], v[136:139], v[190:193], v[24:27]
	v_mfma_f32_16x16x32_bf16 v[20:23], v[128:131], v[198:201], v[20:23]
	v_mfma_f32_16x16x32_bf16 v[12:15], v[136:139], v[198:201], v[12:15]
	v_mfma_f32_16x16x32_bf16 v[60:63], v[132:135], v[164:167], v[60:63]
	v_mfma_f32_16x16x32_bf16 v[56:59], v[140:143], v[164:167], v[56:59]
	v_mfma_f32_16x16x32_bf16 v[48:51], v[132:135], v[172:175], v[48:51]
	v_mfma_f32_16x16x32_bf16 v[40:43], v[140:143], v[172:175], v[40:43]
	v_mfma_f32_16x16x32_bf16 v[32:35], v[132:135], v[194:197], v[32:35]
	v_mfma_f32_16x16x32_bf16 v[24:27], v[140:143], v[194:197], v[24:27]
	v_mfma_f32_16x16x32_bf16 v[20:23], v[132:135], v[216:219], v[20:23]
	v_mfma_f32_16x16x32_bf16 v[12:15], v[140:143], v[216:219], v[12:15]
	s_setprio 0
	s_setprio 1
	v_mfma_f32_16x16x32_bf16 v[52:55], v[144:147], v[160:163], v[52:55]
	v_mfma_f32_16x16x32_bf16 v[44:47], v[152:155], v[160:163], v[44:47]
	v_mfma_f32_16x16x32_bf16 v[36:39], v[144:147], v[168:171], v[36:39]
	v_mfma_f32_16x16x32_bf16 v[28:31], v[152:155], v[168:171], v[28:31]
	v_mfma_f32_16x16x32_bf16 v[16:19], v[144:147], v[190:193], v[16:19]
	v_mfma_f32_16x16x32_bf16 v[8:11], v[152:155], v[190:193], v[8:11]
	v_mfma_f32_16x16x32_bf16 v[4:7], v[144:147], v[198:201], v[4:7]
	v_mfma_f32_16x16x32_bf16 v[0:3], v[152:155], v[198:201], v[0:3]
	v_mfma_f32_16x16x32_bf16 v[52:55], v[148:151], v[164:167], v[52:55]
	v_mfma_f32_16x16x32_bf16 v[44:47], v[156:159], v[164:167], v[44:47]
	v_mfma_f32_16x16x32_bf16 v[36:39], v[148:151], v[172:175], v[36:39]
	v_mfma_f32_16x16x32_bf16 v[28:31], v[156:159], v[172:175], v[28:31]
	v_mfma_f32_16x16x32_bf16 v[16:19], v[148:151], v[194:197], v[16:19]
	v_mfma_f32_16x16x32_bf16 v[8:11], v[156:159], v[194:197], v[8:11]
	v_mfma_f32_16x16x32_bf16 v[4:7], v[148:151], v[216:219], v[4:7]
	v_mfma_f32_16x16x32_bf16 v[0:3], v[156:159], v[216:219], v[0:3]
	s_setprio 0
	s_barrier
	s_add_i32 s52, s52, 2
	s_add_u32 s16, s16, 0x100
	s_addc_u32 s17, s17, 0
	s_add_u32 s50, s50, 0x100
	s_addc_u32 s51, s51, 0
	s_cmp_gt_u32 s52, 41
	s_cbranch_scc0 .LBB0_1324
	s_and_b64 vcc, exec, s[12:13]
	s_cbranch_vccz .LBB0_1327
	s_barrier

.Llsb_skip_19:
.LBB0_2240:
	ds_read_b128 v[128:131], v212
	ds_read_b128 v[132:135], v212 offset:1024
	ds_read_b128 v[136:139], v212 offset:2048
	ds_read_b128 v[140:143], v212 offset:3072
	ds_read_b128 v[144:147], v213
	ds_read_b128 v[148:151], v213 offset:1024
	ds_read_b128 v[152:155], v213 offset:2048
	ds_read_b128 v[156:159], v213 offset:3072
	s_add_u32 s24, s22, 0xfffc0080
	s_addc_u32 s25, s23, -1
	s_cmp_eq_u32 s56, 12
	s_cselect_b32 s27, s15, s25
	s_cselect_b32 s26, s52, s24
	s_cselect_b32 s25, s13, s55
	s_cselect_b32 s24, s53, s54
	s_add_i32 m0, s30, 0xc000
	ds_read_b128 v[160:163], v214
	ds_read_b128 v[164:167], v214 offset:1024
	ds_read_b128 v[168:171], v214 offset:2048
	ds_read_b128 v[172:175], v214 offset:3072
	ds_read_b128 v[190:193], v214 offset:4096
	ds_read_b128 v[194:197], v214 offset:5120
	ds_read_b128 v[198:201], v214 offset:6144
	ds_read_b128 v[216:219], v214 offset:7168
	global_load_lds_dwordx4 v182, s[22:23]
	s_add_i32 m0, s30, 0xe000
	s_nop 0
	global_load_lds_dwordx4 v184, s[22:23]
	s_waitcnt vmcnt(8)
	s_waitcnt lgkmcnt(0)
	s_barrier
	s_setprio 1
	s_waitcnt lgkmcnt(0)
	v_mfma_f32_16x16x32_bf16 v[124:127], v[128:131], v[160:163], v[124:127]
	v_mfma_f32_16x16x32_bf16 v[120:123], v[136:139], v[160:163], v[120:123]
	v_mfma_f32_16x16x32_bf16 v[112:115], v[128:131], v[168:171], v[112:115]
	v_mfma_f32_16x16x32_bf16 v[104:107], v[136:139], v[168:171], v[104:107]
	v_mfma_f32_16x16x32_bf16 v[96:99], v[128:131], v[190:193], v[96:99]
	v_mfma_f32_16x16x32_bf16 v[88:91], v[136:139], v[190:193], v[88:91]
	v_mfma_f32_16x16x32_bf16 v[84:87], v[128:131], v[198:201], v[84:87]
	v_mfma_f32_16x16x32_bf16 v[76:79], v[136:139], v[198:201], v[76:79]
	v_mfma_f32_16x16x32_bf16 v[124:127], v[132:135], v[164:167], v[124:127]
	v_mfma_f32_16x16x32_bf16 v[120:123], v[140:143], v[164:167], v[120:123]
	v_mfma_f32_16x16x32_bf16 v[112:115], v[132:135], v[172:175], v[112:115]
	v_mfma_f32_16x16x32_bf16 v[104:107], v[140:143], v[172:175], v[104:107]
	v_mfma_f32_16x16x32_bf16 v[96:99], v[132:135], v[194:197], v[96:99]
	v_mfma_f32_16x16x32_bf16 v[88:91], v[140:143], v[194:197], v[88:91]
	v_mfma_f32_16x16x32_bf16 v[84:87], v[132:135], v[216:219], v[84:87]
	v_mfma_f32_16x16x32_bf16 v[76:79], v[140:143], v[216:219], v[76:79]
	s_setprio 0
	s_setprio 1
	v_mfma_f32_16x16x32_bf16 v[116:119], v[144:147], v[160:163], v[116:119]
	v_mfma_f32_16x16x32_bf16 v[108:111], v[152:155], v[160:163], v[108:111]
	v_mfma_f32_16x16x32_bf16 v[100:103], v[144:147], v[168:171], v[100:103]
	v_mfma_f32_16x16x32_bf16 v[92:95], v[152:155], v[168:171], v[92:95]
	v_mfma_f32_16x16x32_bf16 v[80:83], v[144:147], v[190:193], v[80:83]
	v_mfma_f32_16x16x32_bf16 v[72:75], v[152:155], v[190:193], v[72:75]
	v_mfma_f32_16x16x32_bf16 v[68:71], v[144:147], v[198:201], v[68:71]
	v_mfma_f32_16x16x32_bf16 v[64:67], v[152:155], v[198:201], v[64:67]
	v_mfma_f32_16x16x32_bf16 v[116:119], v[148:151], v[164:167], v[116:119]
	v_mfma_f32_16x16x32_bf16 v[108:111], v[156:159], v[164:167], v[108:111]
	v_mfma_f32_16x16x32_bf16 v[100:103], v[148:151], v[172:175], v[100:103]
	v_mfma_f32_16x16x32_bf16 v[92:95], v[156:159], v[172:175], v[92:95]
	v_mfma_f32_16x16x32_bf16 v[80:83], v[148:151], v[194:197], v[80:83]
	v_mfma_f32_16x16x32_bf16 v[72:75], v[156:159], v[194:197], v[72:75]
	v_mfma_f32_16x16x32_bf16 v[68:71], v[148:151], v[216:219], v[68:71]
	v_mfma_f32_16x16x32_bf16 v[64:67], v[156:159], v[216:219], v[64:67]
	s_setprio 0
	s_barrier
	s_add_i32 s57, s45, s29
	v_lshl_add_u64 v[202:203], s[24:25], 0, v[176:177]
	s_mov_b32 m0, s57
	ds_read_b128 v[160:163], v214 offset:16384
	ds_read_b128 v[164:167], v214 offset:17408
	ds_read_b128 v[168:171], v214 offset:18432
	ds_read_b128 v[172:175], v214 offset:19456
	ds_read_b128 v[190:193], v214 offset:20480
	ds_read_b128 v[194:197], v214 offset:21504
	ds_read_b128 v[198:201], v214 offset:22528
	ds_read_b128 v[216:219], v214 offset:23552
	global_load_lds_dwordx4 v176, s[24:25]
	s_add_i32 m0, s57, 0x2000
	s_add_u32 s58, s24, 0x40000
	v_lshl_add_u64 v[220:221], s[24:25], 0, v[178:179]
	s_addc_u32 s59, s25, 0
	s_add_i32 s57, s46, s29
	global_load_lds_dwordx4 v178, s[24:25]
	s_mov_b32 m0, s57
	v_lshl_add_u64 v[224:225], s[26:27], 0, v[178:179]
	global_load_lds_dwordx4 v176, s[58:59]
	s_add_i32 m0, s57, 0x2000
	s_nop 0
	global_load_lds_dwordx4 v178, s[58:59]
	v_lshl_add_u64 v[222:223], s[26:27], 0, v[176:177]
	s_mov_b32 m0, s30
	s_nop 0
	global_load_lds_dwordx4 v176, s[26:27]
	s_mov_b32 m0, s31
	s_nop 0
	global_load_lds_dwordx4 v178, s[26:27]
	s_waitcnt vmcnt(8)
	s_waitcnt lgkmcnt(0)
	s_barrier
	s_setprio 1
	s_waitcnt lgkmcnt(0)
	v_mfma_f32_16x16x32_bf16 v[60:63], v[128:131], v[160:163], v[60:63]
	v_mfma_f32_16x16x32_bf16 v[56:59], v[136:139], v[160:163], v[56:59]
	v_mfma_f32_16x16x32_bf16 v[48:51], v[128:131], v[168:171], v[48:51]
	v_mfma_f32_16x16x32_bf16 v[40:43], v[136:139], v[168:171], v[40:43]
	v_mfma_f32_16x16x32_bf16 v[32:35], v[128:131], v[190:193], v[32:35]
	v_mfma_f32_16x16x32_bf16 v[24:27], v[136:139], v[190:193], v[24:27]
	v_mfma_f32_16x16x32_bf16 v[20:23], v[128:131], v[198:201], v[20:23]
	v_mfma_f32_16x16x32_bf16 v[12:15], v[136:139], v[198:201], v[12:15]
	v_mfma_f32_16x16x32_bf16 v[60:63], v[132:135], v[164:167], v[60:63]
	v_mfma_f32_16x16x32_bf16 v[56:59], v[140:143], v[164:167], v[56:59]
	v_mfma_f32_16x16x32_bf16 v[48:51], v[132:135], v[172:175], v[48:51]
	v_mfma_f32_16x16x32_bf16 v[40:43], v[140:143], v[172:175], v[40:43]
	v_mfma_f32_16x16x32_bf16 v[32:35], v[132:135], v[194:197], v[32:35]
	v_mfma_f32_16x16x32_bf16 v[24:27], v[140:143], v[194:197], v[24:27]
	v_mfma_f32_16x16x32_bf16 v[20:23], v[132:135], v[216:219], v[20:23]
	v_mfma_f32_16x16x32_bf16 v[12:15], v[140:143], v[216:219], v[12:15]
	s_setprio 0
	s_setprio 1
	v_mfma_f32_16x16x32_bf16 v[52:55], v[144:147], v[160:163], v[52:55]
	v_mfma_f32_16x16x32_bf16 v[44:47], v[152:155], v[160:163], v[44:47]
	v_mfma_f32_16x16x32_bf16 v[36:39], v[144:147], v[168:171], v[36:39]
	v_mfma_f32_16x16x32_bf16 v[28:31], v[152:155], v[168:171], v[28:31]
	v_mfma_f32_16x16x32_bf16 v[16:19], v[144:147], v[190:193], v[16:19]
	v_mfma_f32_16x16x32_bf16 v[8:11], v[152:155], v[190:193], v[8:11]
	v_mfma_f32_16x16x32_bf16 v[4:7], v[144:147], v[198:201], v[4:7]
	v_mfma_f32_16x16x32_bf16 v[0:3], v[152:155], v[198:201], v[0:3]
	v_mfma_f32_16x16x32_bf16 v[52:55], v[148:151], v[164:167], v[52:55]
	v_mfma_f32_16x16x32_bf16 v[44:47], v[156:159], v[164:167], v[44:47]
	v_mfma_f32_16x16x32_bf16 v[36:39], v[148:151], v[172:175], v[36:39]
	v_mfma_f32_16x16x32_bf16 v[28:31], v[156:159], v[172:175], v[28:31]
	v_mfma_f32_16x16x32_bf16 v[16:19], v[148:151], v[194:197], v[16:19]
	v_mfma_f32_16x16x32_bf16 v[8:11], v[156:159], v[194:197], v[8:11]
	v_mfma_f32_16x16x32_bf16 v[4:7], v[148:151], v[216:219], v[4:7]
	v_mfma_f32_16x16x32_bf16 v[0:3], v[156:159], v[216:219], v[0:3]
	s_setprio 0
	s_barrier
	s_add_i32 s57, 0, 0x18000
	s_add_i32 s58, 0, 0x1c000
	v_add_u32_e32 v140, s57, v210
	v_add_u32_e32 v156, s58, v210
	ds_read_b128 v[128:131], v140
	ds_read_b128 v[132:135], v140 offset:1024
	ds_read_b128 v[136:139], v140 offset:2048
	ds_read_b128 v[140:143], v140 offset:3072
	ds_read_b128 v[144:147], v156
	ds_read_b128 v[148:151], v156 offset:1024
	ds_read_b128 v[152:155], v156 offset:2048
	ds_read_b128 v[156:159], v156 offset:3072
	s_add_u32 s26, s26, 0x40000
	s_addc_u32 s27, s27, 0
	s_mov_b32 m0, s34
	ds_read_b128 v[160:163], v214 offset:32768
	ds_read_b128 v[164:167], v214 offset:33792
	ds_read_b128 v[168:171], v214 offset:34816
	ds_read_b128 v[172:175], v214 offset:35840
	ds_read_b128 v[190:193], v214 offset:36864
	ds_read_b128 v[194:197], v214 offset:37888
	ds_read_b128 v[198:201], v214 offset:38912
	ds_read_b128 v[216:219], v214 offset:39936
	global_load_lds_dwordx4 v176, s[26:27]
	s_mov_b32 m0, s35
	s_nop 0
	global_load_lds_dwordx4 v178, s[26:27]
	s_waitcnt vmcnt(8)
	s_waitcnt lgkmcnt(0)
	s_barrier
	s_setprio 1
	s_waitcnt lgkmcnt(0)
	v_mfma_f32_16x16x32_bf16 v[124:127], v[128:131], v[160:163], v[124:127]
	v_mfma_f32_16x16x32_bf16 v[120:123], v[136:139], v[160:163], v[120:123]
	v_mfma_f32_16x16x32_bf16 v[112:115], v[128:131], v[168:171], v[112:115]
	v_mfma_f32_16x16x32_bf16 v[104:107], v[136:139], v[168:171], v[104:107]
	v_mfma_f32_16x16x32_bf16 v[96:99], v[128:131], v[190:193], v[96:99]
	v_mfma_f32_16x16x32_bf16 v[88:91], v[136:139], v[190:193], v[88:91]
	v_mfma_f32_16x16x32_bf16 v[84:87], v[128:131], v[198:201], v[84:87]
	v_mfma_f32_16x16x32_bf16 v[76:79], v[136:139], v[198:201], v[76:79]
	v_mfma_f32_16x16x32_bf16 v[124:127], v[132:135], v[164:167], v[124:127]
	v_mfma_f32_16x16x32_bf16 v[120:123], v[140:143], v[164:167], v[120:123]
	v_mfma_f32_16x16x32_bf16 v[112:115], v[132:135], v[172:175], v[112:115]
	v_mfma_f32_16x16x32_bf16 v[104:107], v[140:143], v[172:175], v[104:107]
	v_mfma_f32_16x16x32_bf16 v[96:99], v[132:135], v[194:197], v[96:99]
	v_mfma_f32_16x16x32_bf16 v[88:91], v[140:143], v[194:197], v[88:91]
	v_mfma_f32_16x16x32_bf16 v[84:87], v[132:135], v[216:219], v[84:87]
	v_mfma_f32_16x16x32_bf16 v[76:79], v[140:143], v[216:219], v[76:79]
	s_setprio 0
	s_setprio 1
	v_mfma_f32_16x16x32_bf16 v[116:119], v[144:147], v[160:163], v[116:119]
	v_mfma_f32_16x16x32_bf16 v[108:111], v[152:155], v[160:163], v[108:111]
	v_mfma_f32_16x16x32_bf16 v[100:103], v[144:147], v[168:171], v[100:103]
	v_mfma_f32_16x16x32_bf16 v[92:95], v[152:155], v[168:171], v[92:95]
	v_mfma_f32_16x16x32_bf16 v[80:83], v[144:147], v[190:193], v[80:83]
	v_mfma_f32_16x16x32_bf16 v[72:75], v[152:155], v[190:193], v[72:75]
	v_mfma_f32_16x16x32_bf16 v[68:71], v[144:147], v[198:201], v[68:71]
	v_mfma_f32_16x16x32_bf16 v[64:67], v[152:155], v[198:201], v[64:67]
	v_mfma_f32_16x16x32_bf16 v[116:119], v[148:151], v[164:167], v[116:119]
	v_mfma_f32_16x16x32_bf16 v[108:111], v[156:159], v[164:167], v[108:111]
	v_mfma_f32_16x16x32_bf16 v[100:103], v[148:151], v[172:175], v[100:103]
	v_mfma_f32_16x16x32_bf16 v[92:95], v[156:159], v[172:175], v[92:95]
	v_mfma_f32_16x16x32_bf16 v[80:83], v[148:151], v[194:197], v[80:83]
	v_mfma_f32_16x16x32_bf16 v[72:75], v[156:159], v[194:197], v[72:75]
	v_mfma_f32_16x16x32_bf16 v[68:71], v[148:151], v[216:219], v[68:71]
	v_mfma_f32_16x16x32_bf16 v[64:67], v[156:159], v[216:219], v[64:67]
	s_setprio 0
	s_barrier
	s_add_i32 s26, s57, s29
	v_lshl_add_u64 v[202:203], v[202:203], 0, s[8:9]
	s_mov_b32 m0, s26
	ds_read_b128 v[160:163], v214 offset:49152
	ds_read_b128 v[164:167], v214 offset:50176
	ds_read_b128 v[168:171], v214 offset:51200
	ds_read_b128 v[172:175], v214 offset:52224
	ds_read_b128 v[190:193], v214 offset:53248
	ds_read_b128 v[194:197], v214 offset:54272
	ds_read_b128 v[198:201], v214 offset:55296
	ds_read_b128 v[216:219], v214 offset:56320
	global_load_lds_dwordx4 v[202:203], off
	s_add_i32 m0, s26, 0x2000
	s_add_u32 s24, s24, 0x40080
	v_lshl_add_u64 v[202:203], v[220:221], 0, s[8:9]
	s_addc_u32 s25, s25, 0
	s_add_i32 s26, s58, s29
	global_load_lds_dwordx4 v[202:203], off
	s_mov_b32 m0, s26
	s_nop 0
	global_load_lds_dwordx4 v176, s[24:25]
	s_add_i32 m0, s26, 0x2000
	s_nop 0
	global_load_lds_dwordx4 v178, s[24:25]
	v_lshl_add_u64 v[202:203], v[222:223], 0, s[8:9]
	s_mov_b32 m0, s42
	s_nop 0
	global_load_lds_dwordx4 v[202:203], off
	v_lshl_add_u64 v[202:203], v[224:225], 0, s[8:9]
	s_mov_b32 m0, s43
	s_nop 0
	global_load_lds_dwordx4 v[202:203], off
	s_waitcnt vmcnt(8)
	s_waitcnt lgkmcnt(0)
	s_barrier
	s_setprio 1
	s_waitcnt lgkmcnt(0)
	v_mfma_f32_16x16x32_bf16 v[60:63], v[128:131], v[160:163], v[60:63]
	v_mfma_f32_16x16x32_bf16 v[56:59], v[136:139], v[160:163], v[56:59]
	v_mfma_f32_16x16x32_bf16 v[48:51], v[128:131], v[168:171], v[48:51]
	v_mfma_f32_16x16x32_bf16 v[40:43], v[136:139], v[168:171], v[40:43]
	v_mfma_f32_16x16x32_bf16 v[32:35], v[128:131], v[190:193], v[32:35]
	v_mfma_f32_16x16x32_bf16 v[24:27], v[136:139], v[190:193], v[24:27]
	v_mfma_f32_16x16x32_bf16 v[20:23], v[128:131], v[198:201], v[20:23]
	v_mfma_f32_16x16x32_bf16 v[12:15], v[136:139], v[198:201], v[12:15]
	v_mfma_f32_16x16x32_bf16 v[60:63], v[132:135], v[164:167], v[60:63]
	v_mfma_f32_16x16x32_bf16 v[56:59], v[140:143], v[164:167], v[56:59]
	v_mfma_f32_16x16x32_bf16 v[48:51], v[132:135], v[172:175], v[48:51]
	v_mfma_f32_16x16x32_bf16 v[40:43], v[140:143], v[172:175], v[40:43]
	v_mfma_f32_16x16x32_bf16 v[32:35], v[132:135], v[194:197], v[32:35]
	v_mfma_f32_16x16x32_bf16 v[24:27], v[140:143], v[194:197], v[24:27]
	v_mfma_f32_16x16x32_bf16 v[20:23], v[132:135], v[216:219], v[20:23]
	v_mfma_f32_16x16x32_bf16 v[12:15], v[140:143], v[216:219], v[12:15]
	s_setprio 0
	s_setprio 1
	v_mfma_f32_16x16x32_bf16 v[52:55], v[144:147], v[160:163], v[52:55]
	v_mfma_f32_16x16x32_bf16 v[44:47], v[152:155], v[160:163], v[44:47]
	v_mfma_f32_16x16x32_bf16 v[36:39], v[144:147], v[168:171], v[36:39]
	v_mfma_f32_16x16x32_bf16 v[28:31], v[152:155], v[168:171], v[28:31]
	v_mfma_f32_16x16x32_bf16 v[16:19], v[144:147], v[190:193], v[16:19]
	v_mfma_f32_16x16x32_bf16 v[8:11], v[152:155], v[190:193], v[8:11]
	v_mfma_f32_16x16x32_bf16 v[4:7], v[144:147], v[198:201], v[4:7]
	v_mfma_f32_16x16x32_bf16 v[0:3], v[152:155], v[198:201], v[0:3]
	v_mfma_f32_16x16x32_bf16 v[52:55], v[148:151], v[164:167], v[52:55]
	v_mfma_f32_16x16x32_bf16 v[44:47], v[156:159], v[164:167], v[44:47]
	v_mfma_f32_16x16x32_bf16 v[36:39], v[148:151], v[172:175], v[36:39]
	v_mfma_f32_16x16x32_bf16 v[28:31], v[156:159], v[172:175], v[28:31]
	v_mfma_f32_16x16x32_bf16 v[16:19], v[148:151], v[194:197], v[16:19]
	v_mfma_f32_16x16x32_bf16 v[8:11], v[156:159], v[194:197], v[8:11]
	v_mfma_f32_16x16x32_bf16 v[4:7], v[148:151], v[216:219], v[4:7]
	v_mfma_f32_16x16x32_bf16 v[0:3], v[156:159], v[216:219], v[0:3]
	s_setprio 0
	s_barrier
	s_add_i32 s56, s56, 2
	s_add_u32 s22, s22, 0x100
	s_addc_u32 s23, s23, 0
	s_add_u32 s54, s54, 0x100
	s_addc_u32 s55, s55, 0
	s_cmp_gt_u32 s56, 13
	s_cbranch_scc0 .LBB0_2240
	s_and_b64 vcc, exec, s[10:11]
	s_cbranch_vccz .LBB0_2243
	s_barrier

.Llsb_skip_21:
.LBB0_2476:
	ds_read_b128 v[128:131], v212
	ds_read_b128 v[132:135], v212 offset:1024
	ds_read_b128 v[136:139], v212 offset:2048
	ds_read_b128 v[140:143], v212 offset:3072
	ds_read_b128 v[144:147], v213
	ds_read_b128 v[148:151], v213 offset:1024
	ds_read_b128 v[152:155], v213 offset:2048
	ds_read_b128 v[156:159], v213 offset:3072
	s_add_u32 s18, s16, 0xfff50080
	s_addc_u32 s19, s17, -1
	s_cmp_eq_u32 s52, 40
	s_cselect_b32 s21, s5, s19
	s_cselect_b32 s20, s4, s18
	s_cselect_b32 s19, s15, s51
	s_cselect_b32 s18, s14, s50
	s_add_i32 m0, s23, 0xc000
	ds_read_b128 v[160:163], v214
	ds_read_b128 v[164:167], v214 offset:1024
	ds_read_b128 v[168:171], v214 offset:2048
	ds_read_b128 v[172:175], v214 offset:3072
	ds_read_b128 v[190:193], v214 offset:4096
	ds_read_b128 v[194:197], v214 offset:5120
	ds_read_b128 v[198:201], v214 offset:6144
	ds_read_b128 v[216:219], v214 offset:7168
	global_load_lds_dwordx4 v182, s[16:17]
	s_add_i32 m0, s23, 0xe000
	s_nop 0
	global_load_lds_dwordx4 v184, s[16:17]
	s_waitcnt vmcnt(8)
	s_waitcnt lgkmcnt(0)
	s_barrier
	s_setprio 1
	s_waitcnt lgkmcnt(0)
	v_mfma_f32_16x16x32_bf16 v[124:127], v[128:131], v[160:163], v[124:127]
	v_mfma_f32_16x16x32_bf16 v[120:123], v[136:139], v[160:163], v[120:123]
	v_mfma_f32_16x16x32_bf16 v[112:115], v[128:131], v[168:171], v[112:115]
	v_mfma_f32_16x16x32_bf16 v[104:107], v[136:139], v[168:171], v[104:107]
	v_mfma_f32_16x16x32_bf16 v[96:99], v[128:131], v[190:193], v[96:99]
	v_mfma_f32_16x16x32_bf16 v[88:91], v[136:139], v[190:193], v[88:91]
	v_mfma_f32_16x16x32_bf16 v[84:87], v[128:131], v[198:201], v[84:87]
	v_mfma_f32_16x16x32_bf16 v[76:79], v[136:139], v[198:201], v[76:79]
	v_mfma_f32_16x16x32_bf16 v[124:127], v[132:135], v[164:167], v[124:127]
	v_mfma_f32_16x16x32_bf16 v[120:123], v[140:143], v[164:167], v[120:123]
	v_mfma_f32_16x16x32_bf16 v[112:115], v[132:135], v[172:175], v[112:115]
	v_mfma_f32_16x16x32_bf16 v[104:107], v[140:143], v[172:175], v[104:107]
	v_mfma_f32_16x16x32_bf16 v[96:99], v[132:135], v[194:197], v[96:99]
	v_mfma_f32_16x16x32_bf16 v[88:91], v[140:143], v[194:197], v[88:91]
	v_mfma_f32_16x16x32_bf16 v[84:87], v[132:135], v[216:219], v[84:87]
	v_mfma_f32_16x16x32_bf16 v[76:79], v[140:143], v[216:219], v[76:79]
	s_setprio 0
	s_setprio 1
	v_mfma_f32_16x16x32_bf16 v[116:119], v[144:147], v[160:163], v[116:119]
	v_mfma_f32_16x16x32_bf16 v[108:111], v[152:155], v[160:163], v[108:111]
	v_mfma_f32_16x16x32_bf16 v[100:103], v[144:147], v[168:171], v[100:103]
	v_mfma_f32_16x16x32_bf16 v[92:95], v[152:155], v[168:171], v[92:95]
	v_mfma_f32_16x16x32_bf16 v[80:83], v[144:147], v[190:193], v[80:83]
	v_mfma_f32_16x16x32_bf16 v[72:75], v[152:155], v[190:193], v[72:75]
	v_mfma_f32_16x16x32_bf16 v[68:71], v[144:147], v[198:201], v[68:71]
	v_mfma_f32_16x16x32_bf16 v[64:67], v[152:155], v[198:201], v[64:67]
	v_mfma_f32_16x16x32_bf16 v[116:119], v[148:151], v[164:167], v[116:119]
	v_mfma_f32_16x16x32_bf16 v[108:111], v[156:159], v[164:167], v[108:111]
	v_mfma_f32_16x16x32_bf16 v[100:103], v[148:151], v[172:175], v[100:103]
	v_mfma_f32_16x16x32_bf16 v[92:95], v[156:159], v[172:175], v[92:95]
	v_mfma_f32_16x16x32_bf16 v[80:83], v[148:151], v[194:197], v[80:83]
	v_mfma_f32_16x16x32_bf16 v[72:75], v[156:159], v[194:197], v[72:75]
	v_mfma_f32_16x16x32_bf16 v[68:71], v[148:151], v[216:219], v[68:71]
	v_mfma_f32_16x16x32_bf16 v[64:67], v[156:159], v[216:219], v[64:67]
	s_setprio 0
	s_barrier
	s_add_i32 s53, s35, s22
	v_lshl_add_u64 v[202:203], s[18:19], 0, v[176:177]
	s_mov_b32 m0, s53
	ds_read_b128 v[160:163], v214 offset:16384
	ds_read_b128 v[164:167], v214 offset:17408
	ds_read_b128 v[168:171], v214 offset:18432
	ds_read_b128 v[172:175], v214 offset:19456
	ds_read_b128 v[190:193], v214 offset:20480
	ds_read_b128 v[194:197], v214 offset:21504
	ds_read_b128 v[198:201], v214 offset:22528
	ds_read_b128 v[216:219], v214 offset:23552
	global_load_lds_dwordx4 v176, s[18:19]
	s_add_i32 m0, s53, 0x2000
	s_add_u32 s54, s18, 0xb0000
	v_lshl_add_u64 v[220:221], s[18:19], 0, v[178:179]
	s_addc_u32 s55, s19, 0
	s_add_i32 s53, s36, s22
	global_load_lds_dwordx4 v178, s[18:19]
	s_mov_b32 m0, s53
	v_lshl_add_u64 v[224:225], s[20:21], 0, v[178:179]
	global_load_lds_dwordx4 v176, s[54:55]
	s_add_i32 m0, s53, 0x2000
	s_nop 0
	global_load_lds_dwordx4 v178, s[54:55]
	v_lshl_add_u64 v[222:223], s[20:21], 0, v[176:177]
	s_mov_b32 m0, s23
	s_nop 0
	global_load_lds_dwordx4 v176, s[20:21]
	s_mov_b32 m0, s24
	s_nop 0
	global_load_lds_dwordx4 v178, s[20:21]
	s_waitcnt vmcnt(8)
	s_waitcnt lgkmcnt(0)
	s_barrier
	s_setprio 1
	s_waitcnt lgkmcnt(0)
	v_mfma_f32_16x16x32_bf16 v[60:63], v[128:131], v[160:163], v[60:63]
	v_mfma_f32_16x16x32_bf16 v[56:59], v[136:139], v[160:163], v[56:59]
	v_mfma_f32_16x16x32_bf16 v[48:51], v[128:131], v[168:171], v[48:51]
	v_mfma_f32_16x16x32_bf16 v[40:43], v[136:139], v[168:171], v[40:43]
	v_mfma_f32_16x16x32_bf16 v[32:35], v[128:131], v[190:193], v[32:35]
	v_mfma_f32_16x16x32_bf16 v[24:27], v[136:139], v[190:193], v[24:27]
	v_mfma_f32_16x16x32_bf16 v[20:23], v[128:131], v[198:201], v[20:23]
	v_mfma_f32_16x16x32_bf16 v[12:15], v[136:139], v[198:201], v[12:15]
	v_mfma_f32_16x16x32_bf16 v[60:63], v[132:135], v[164:167], v[60:63]
	v_mfma_f32_16x16x32_bf16 v[56:59], v[140:143], v[164:167], v[56:59]
	v_mfma_f32_16x16x32_bf16 v[48:51], v[132:135], v[172:175], v[48:51]
	v_mfma_f32_16x16x32_bf16 v[40:43], v[140:143], v[172:175], v[40:43]
	v_mfma_f32_16x16x32_bf16 v[32:35], v[132:135], v[194:197], v[32:35]
	v_mfma_f32_16x16x32_bf16 v[24:27], v[140:143], v[194:197], v[24:27]
	v_mfma_f32_16x16x32_bf16 v[20:23], v[132:135], v[216:219], v[20:23]
	v_mfma_f32_16x16x32_bf16 v[12:15], v[140:143], v[216:219], v[12:15]
	s_setprio 0
	s_setprio 1
	v_mfma_f32_16x16x32_bf16 v[52:55], v[144:147], v[160:163], v[52:55]
	v_mfma_f32_16x16x32_bf16 v[44:47], v[152:155], v[160:163], v[44:47]
	v_mfma_f32_16x16x32_bf16 v[36:39], v[144:147], v[168:171], v[36:39]
	v_mfma_f32_16x16x32_bf16 v[28:31], v[152:155], v[168:171], v[28:31]
	v_mfma_f32_16x16x32_bf16 v[16:19], v[144:147], v[190:193], v[16:19]
	v_mfma_f32_16x16x32_bf16 v[8:11], v[152:155], v[190:193], v[8:11]
	v_mfma_f32_16x16x32_bf16 v[4:7], v[144:147], v[198:201], v[4:7]
	v_mfma_f32_16x16x32_bf16 v[0:3], v[152:155], v[198:201], v[0:3]
	v_mfma_f32_16x16x32_bf16 v[52:55], v[148:151], v[164:167], v[52:55]
	v_mfma_f32_16x16x32_bf16 v[44:47], v[156:159], v[164:167], v[44:47]
	v_mfma_f32_16x16x32_bf16 v[36:39], v[148:151], v[172:175], v[36:39]
	v_mfma_f32_16x16x32_bf16 v[28:31], v[156:159], v[172:175], v[28:31]
	v_mfma_f32_16x16x32_bf16 v[16:19], v[148:151], v[194:197], v[16:19]
	v_mfma_f32_16x16x32_bf16 v[8:11], v[156:159], v[194:197], v[8:11]
	v_mfma_f32_16x16x32_bf16 v[4:7], v[148:151], v[216:219], v[4:7]
	v_mfma_f32_16x16x32_bf16 v[0:3], v[156:159], v[216:219], v[0:3]
	s_setprio 0
	s_barrier
	s_add_i32 s53, 0, 0x18000
	s_add_i32 s54, 0, 0x1c000
	v_add_u32_e32 v140, s53, v210
	v_add_u32_e32 v156, s54, v210
	ds_read_b128 v[128:131], v140
	ds_read_b128 v[132:135], v140 offset:1024
	ds_read_b128 v[136:139], v140 offset:2048
	ds_read_b128 v[140:143], v140 offset:3072
	ds_read_b128 v[144:147], v156
	ds_read_b128 v[148:151], v156 offset:1024
	ds_read_b128 v[152:155], v156 offset:2048
	ds_read_b128 v[156:159], v156 offset:3072
	s_add_u32 s20, s20, 0xb0000
	s_addc_u32 s21, s21, 0
	s_mov_b32 m0, s25
	ds_read_b128 v[160:163], v214 offset:32768
	ds_read_b128 v[164:167], v214 offset:33792
	ds_read_b128 v[168:171], v214 offset:34816
	ds_read_b128 v[172:175], v214 offset:35840
	ds_read_b128 v[190:193], v214 offset:36864
	ds_read_b128 v[194:197], v214 offset:37888
	ds_read_b128 v[198:201], v214 offset:38912
	ds_read_b128 v[216:219], v214 offset:39936
	global_load_lds_dwordx4 v176, s[20:21]
	s_mov_b32 m0, s26
	s_nop 0
	global_load_lds_dwordx4 v178, s[20:21]
	s_waitcnt vmcnt(8)
	s_waitcnt lgkmcnt(0)
	s_barrier
	s_setprio 1
	s_waitcnt lgkmcnt(0)
	v_mfma_f32_16x16x32_bf16 v[124:127], v[128:131], v[160:163], v[124:127]
	v_mfma_f32_16x16x32_bf16 v[120:123], v[136:139], v[160:163], v[120:123]
	v_mfma_f32_16x16x32_bf16 v[112:115], v[128:131], v[168:171], v[112:115]
	v_mfma_f32_16x16x32_bf16 v[104:107], v[136:139], v[168:171], v[104:107]
	v_mfma_f32_16x16x32_bf16 v[96:99], v[128:131], v[190:193], v[96:99]
	v_mfma_f32_16x16x32_bf16 v[88:91], v[136:139], v[190:193], v[88:91]
	v_mfma_f32_16x16x32_bf16 v[84:87], v[128:131], v[198:201], v[84:87]
	v_mfma_f32_16x16x32_bf16 v[76:79], v[136:139], v[198:201], v[76:79]
	v_mfma_f32_16x16x32_bf16 v[124:127], v[132:135], v[164:167], v[124:127]
	v_mfma_f32_16x16x32_bf16 v[120:123], v[140:143], v[164:167], v[120:123]
	v_mfma_f32_16x16x32_bf16 v[112:115], v[132:135], v[172:175], v[112:115]
	v_mfma_f32_16x16x32_bf16 v[104:107], v[140:143], v[172:175], v[104:107]
	v_mfma_f32_16x16x32_bf16 v[96:99], v[132:135], v[194:197], v[96:99]
	v_mfma_f32_16x16x32_bf16 v[88:91], v[140:143], v[194:197], v[88:91]
	v_mfma_f32_16x16x32_bf16 v[84:87], v[132:135], v[216:219], v[84:87]
	v_mfma_f32_16x16x32_bf16 v[76:79], v[140:143], v[216:219], v[76:79]
	s_setprio 0
	s_setprio 1
	v_mfma_f32_16x16x32_bf16 v[116:119], v[144:147], v[160:163], v[116:119]
	v_mfma_f32_16x16x32_bf16 v[108:111], v[152:155], v[160:163], v[108:111]
	v_mfma_f32_16x16x32_bf16 v[100:103], v[144:147], v[168:171], v[100:103]
	v_mfma_f32_16x16x32_bf16 v[92:95], v[152:155], v[168:171], v[92:95]
	v_mfma_f32_16x16x32_bf16 v[80:83], v[144:147], v[190:193], v[80:83]
	v_mfma_f32_16x16x32_bf16 v[72:75], v[152:155], v[190:193], v[72:75]
	v_mfma_f32_16x16x32_bf16 v[68:71], v[144:147], v[198:201], v[68:71]
	v_mfma_f32_16x16x32_bf16 v[64:67], v[152:155], v[198:201], v[64:67]
	v_mfma_f32_16x16x32_bf16 v[116:119], v[148:151], v[164:167], v[116:119]
	v_mfma_f32_16x16x32_bf16 v[108:111], v[156:159], v[164:167], v[108:111]
	v_mfma_f32_16x16x32_bf16 v[100:103], v[148:151], v[172:175], v[100:103]
	v_mfma_f32_16x16x32_bf16 v[92:95], v[156:159], v[172:175], v[92:95]
	v_mfma_f32_16x16x32_bf16 v[80:83], v[148:151], v[194:197], v[80:83]
	v_mfma_f32_16x16x32_bf16 v[72:75], v[156:159], v[194:197], v[72:75]
	v_mfma_f32_16x16x32_bf16 v[68:71], v[148:151], v[216:219], v[68:71]
	v_mfma_f32_16x16x32_bf16 v[64:67], v[156:159], v[216:219], v[64:67]
	s_setprio 0
	s_barrier
	s_add_i32 s20, s53, s22
	v_lshl_add_u64 v[202:203], v[202:203], 0, s[10:11]
	s_mov_b32 m0, s20
	ds_read_b128 v[160:163], v214 offset:49152
	ds_read_b128 v[164:167], v214 offset:50176
	ds_read_b128 v[168:171], v214 offset:51200
	ds_read_b128 v[172:175], v214 offset:52224
	ds_read_b128 v[190:193], v214 offset:53248
	ds_read_b128 v[194:197], v214 offset:54272
	ds_read_b128 v[198:201], v214 offset:55296
	ds_read_b128 v[216:219], v214 offset:56320
	global_load_lds_dwordx4 v[202:203], off
	s_add_i32 m0, s20, 0x2000
	s_add_u32 s18, s18, 0xb0080
	v_lshl_add_u64 v[202:203], v[220:221], 0, s[10:11]
	s_addc_u32 s19, s19, 0
	s_add_i32 s20, s54, s22
	global_load_lds_dwordx4 v[202:203], off
	s_mov_b32 m0, s20
	s_nop 0
	global_load_lds_dwordx4 v176, s[18:19]
	s_add_i32 m0, s20, 0x2000
	s_nop 0
	global_load_lds_dwordx4 v178, s[18:19]
	v_lshl_add_u64 v[202:203], v[222:223], 0, s[10:11]
	s_mov_b32 m0, s29
	s_nop 0
	global_load_lds_dwordx4 v[202:203], off
	v_lshl_add_u64 v[202:203], v[224:225], 0, s[10:11]
	s_mov_b32 m0, s30
	s_nop 0
	global_load_lds_dwordx4 v[202:203], off
	s_waitcnt vmcnt(8)
	s_waitcnt lgkmcnt(0)
	s_barrier
	s_setprio 1
	s_waitcnt lgkmcnt(0)
	v_mfma_f32_16x16x32_bf16 v[60:63], v[128:131], v[160:163], v[60:63]
	v_mfma_f32_16x16x32_bf16 v[56:59], v[136:139], v[160:163], v[56:59]
	v_mfma_f32_16x16x32_bf16 v[48:51], v[128:131], v[168:171], v[48:51]
	v_mfma_f32_16x16x32_bf16 v[40:43], v[136:139], v[168:171], v[40:43]
	v_mfma_f32_16x16x32_bf16 v[32:35], v[128:131], v[190:193], v[32:35]
	v_mfma_f32_16x16x32_bf16 v[24:27], v[136:139], v[190:193], v[24:27]
	v_mfma_f32_16x16x32_bf16 v[20:23], v[128:131], v[198:201], v[20:23]
	v_mfma_f32_16x16x32_bf16 v[12:15], v[136:139], v[198:201], v[12:15]
	v_mfma_f32_16x16x32_bf16 v[60:63], v[132:135], v[164:167], v[60:63]
	v_mfma_f32_16x16x32_bf16 v[56:59], v[140:143], v[164:167], v[56:59]
	v_mfma_f32_16x16x32_bf16 v[48:51], v[132:135], v[172:175], v[48:51]
	v_mfma_f32_16x16x32_bf16 v[40:43], v[140:143], v[172:175], v[40:43]
	v_mfma_f32_16x16x32_bf16 v[32:35], v[132:135], v[194:197], v[32:35]
	v_mfma_f32_16x16x32_bf16 v[24:27], v[140:143], v[194:197], v[24:27]
	v_mfma_f32_16x16x32_bf16 v[20:23], v[132:135], v[216:219], v[20:23]
	v_mfma_f32_16x16x32_bf16 v[12:15], v[140:143], v[216:219], v[12:15]
	s_setprio 0
	s_setprio 1
	v_mfma_f32_16x16x32_bf16 v[52:55], v[144:147], v[160:163], v[52:55]
	v_mfma_f32_16x16x32_bf16 v[44:47], v[152:155], v[160:163], v[44:47]
	v_mfma_f32_16x16x32_bf16 v[36:39], v[144:147], v[168:171], v[36:39]
	v_mfma_f32_16x16x32_bf16 v[28:31], v[152:155], v[168:171], v[28:31]
	v_mfma_f32_16x16x32_bf16 v[16:19], v[144:147], v[190:193], v[16:19]
	v_mfma_f32_16x16x32_bf16 v[8:11], v[152:155], v[190:193], v[8:11]
	v_mfma_f32_16x16x32_bf16 v[4:7], v[144:147], v[198:201], v[4:7]
	v_mfma_f32_16x16x32_bf16 v[0:3], v[152:155], v[198:201], v[0:3]
	v_mfma_f32_16x16x32_bf16 v[52:55], v[148:151], v[164:167], v[52:55]
	v_mfma_f32_16x16x32_bf16 v[44:47], v[156:159], v[164:167], v[44:47]
	v_mfma_f32_16x16x32_bf16 v[36:39], v[148:151], v[172:175], v[36:39]
	v_mfma_f32_16x16x32_bf16 v[28:31], v[156:159], v[172:175], v[28:31]
	v_mfma_f32_16x16x32_bf16 v[16:19], v[148:151], v[194:197], v[16:19]
	v_mfma_f32_16x16x32_bf16 v[8:11], v[156:159], v[194:197], v[8:11]
	v_mfma_f32_16x16x32_bf16 v[4:7], v[148:151], v[216:219], v[4:7]
	v_mfma_f32_16x16x32_bf16 v[0:3], v[156:159], v[216:219], v[0:3]
	s_setprio 0
	s_barrier
	s_add_i32 s52, s52, 2
	s_add_u32 s16, s16, 0x100
	s_addc_u32 s17, s17, 0
	s_add_u32 s50, s50, 0x100
	s_addc_u32 s51, s51, 0
	s_cmp_gt_u32 s52, 41
	s_cbranch_scc0 .LBB0_2476
	s_and_b64 vcc, exec, s[12:13]
	s_cbranch_vccz .LBB0_2479
	s_barrier
